# phase 0 de-serialised: adaLN mod K loop (128 strided weight loads per thread were each followed by vmcnt(0): now 3 batches of 16 in flight, counted waits), filter MLP (output layer and both hidden lay
# speedup vs baseline: 1.0181x; 1.0181x over previous
.LBB0_823:
	s_mov_b32 s28, 0x3000
	s_mov_b32 s29, 0
	v_mov_b32_e32 v20, v14
	v_mov_b32_e32 v21, v15
	global_load_dword v48, v[20:21], off
	v_lshl_add_u64 v[20:21], v[20:21], 0, s[28:29]
	global_load_dword v49, v[20:21], off
	v_lshl_add_u64 v[20:21], v[20:21], 0, s[28:29]
	global_load_dword v50, v[20:21], off
	v_lshl_add_u64 v[20:21], v[20:21], 0, s[28:29]
	global_load_dword v51, v[20:21], off
	v_lshl_add_u64 v[20:21], v[20:21], 0, s[28:29]
	global_load_dword v52, v[20:21], off
	v_lshl_add_u64 v[20:21], v[20:21], 0, s[28:29]
	global_load_dword v53, v[20:21], off
	v_lshl_add_u64 v[20:21], v[20:21], 0, s[28:29]
	global_load_dword v54, v[20:21], off
	v_lshl_add_u64 v[20:21], v[20:21], 0, s[28:29]
	global_load_dword v55, v[20:21], off
	v_lshl_add_u64 v[20:21], v[20:21], 0, s[28:29]
	global_load_dword v56, v[20:21], off
	v_lshl_add_u64 v[20:21], v[20:21], 0, s[28:29]
	global_load_dword v57, v[20:21], off
	v_lshl_add_u64 v[20:21], v[20:21], 0, s[28:29]
	global_load_dword v58, v[20:21], off
	v_lshl_add_u64 v[20:21], v[20:21], 0, s[28:29]
	global_load_dword v59, v[20:21], off
	v_lshl_add_u64 v[20:21], v[20:21], 0, s[28:29]
	global_load_dword v60, v[20:21], off
	v_lshl_add_u64 v[20:21], v[20:21], 0, s[28:29]
	global_load_dword v61, v[20:21], off
	v_lshl_add_u64 v[20:21], v[20:21], 0, s[28:29]
	global_load_dword v62, v[20:21], off
	v_lshl_add_u64 v[20:21], v[20:21], 0, s[28:29]
	global_load_dword v63, v[20:21], off
	v_lshl_add_u64 v[20:21], v[20:21], 0, s[28:29]
	global_load_dword v64, v[20:21], off
	v_lshl_add_u64 v[20:21], v[20:21], 0, s[28:29]
	global_load_dword v65, v[20:21], off
	v_lshl_add_u64 v[20:21], v[20:21], 0, s[28:29]
	global_load_dword v66, v[20:21], off
	v_lshl_add_u64 v[20:21], v[20:21], 0, s[28:29]
	global_load_dword v67, v[20:21], off
	v_lshl_add_u64 v[20:21], v[20:21], 0, s[28:29]
	global_load_dword v68, v[20:21], off
	v_lshl_add_u64 v[20:21], v[20:21], 0, s[28:29]
	global_load_dword v69, v[20:21], off
	v_lshl_add_u64 v[20:21], v[20:21], 0, s[28:29]
	global_load_dword v70, v[20:21], off
	v_lshl_add_u64 v[20:21], v[20:21], 0, s[28:29]
	global_load_dword v71, v[20:21], off
	v_lshl_add_u64 v[20:21], v[20:21], 0, s[28:29]
	global_load_dword v72, v[20:21], off
	v_lshl_add_u64 v[20:21], v[20:21], 0, s[28:29]
	global_load_dword v73, v[20:21], off
	v_lshl_add_u64 v[20:21], v[20:21], 0, s[28:29]
	global_load_dword v74, v[20:21], off
	v_lshl_add_u64 v[20:21], v[20:21], 0, s[28:29]
	global_load_dword v75, v[20:21], off
	v_lshl_add_u64 v[20:21], v[20:21], 0, s[28:29]
	global_load_dword v76, v[20:21], off
	v_lshl_add_u64 v[20:21], v[20:21], 0, s[28:29]
	global_load_dword v77, v[20:21], off
	v_lshl_add_u64 v[20:21], v[20:21], 0, s[28:29]
	global_load_dword v78, v[20:21], off
	v_lshl_add_u64 v[20:21], v[20:21], 0, s[28:29]
	global_load_dword v79, v[20:21], off
	v_lshl_add_u64 v[20:21], v[20:21], 0, s[28:29]
	global_load_dword v80, v[20:21], off
	v_lshl_add_u64 v[20:21], v[20:21], 0, s[28:29]
	global_load_dword v81, v[20:21], off
	v_lshl_add_u64 v[20:21], v[20:21], 0, s[28:29]
	global_load_dword v82, v[20:21], off
	v_lshl_add_u64 v[20:21], v[20:21], 0, s[28:29]
	global_load_dword v83, v[20:21], off
	v_lshl_add_u64 v[20:21], v[20:21], 0, s[28:29]
	global_load_dword v84, v[20:21], off
	v_lshl_add_u64 v[20:21], v[20:21], 0, s[28:29]
	global_load_dword v85, v[20:21], off
	v_lshl_add_u64 v[20:21], v[20:21], 0, s[28:29]
	global_load_dword v86, v[20:21], off
	v_lshl_add_u64 v[20:21], v[20:21], 0, s[28:29]
	global_load_dword v87, v[20:21], off
	v_lshl_add_u64 v[20:21], v[20:21], 0, s[28:29]
	global_load_dword v88, v[20:21], off
	v_lshl_add_u64 v[20:21], v[20:21], 0, s[28:29]
	global_load_dword v89, v[20:21], off
	v_lshl_add_u64 v[20:21], v[20:21], 0, s[28:29]
	global_load_dword v90, v[20:21], off
	v_lshl_add_u64 v[20:21], v[20:21], 0, s[28:29]
	global_load_dword v91, v[20:21], off
	v_lshl_add_u64 v[20:21], v[20:21], 0, s[28:29]
	global_load_dword v92, v[20:21], off
	v_lshl_add_u64 v[20:21], v[20:21], 0, s[28:29]
	global_load_dword v93, v[20:21], off
	v_lshl_add_u64 v[20:21], v[20:21], 0, s[28:29]
	global_load_dword v94, v[20:21], off
	v_lshl_add_u64 v[20:21], v[20:21], 0, s[28:29]
	global_load_dword v95, v[20:21], off
	v_lshl_add_u64 v[20:21], v[20:21], 0, s[28:29]
	ds_read_b128 v[26:29], v24 offset:0
	ds_read_b128 v[30:33], v24 offset:4096
	ds_read_b128 v[34:37], v24 offset:8192
	ds_read_b128 v[38:41], v24 offset:12288
	ds_read_b128 v[42:45], v24 offset:16384
	s_waitcnt vmcnt(32)
	ds_read_b128 v[112:115], v24 offset:16
	ds_read_b128 v[116:119], v24 offset:4112
	ds_read_b128 v[120:123], v24 offset:8208
	ds_read_b128 v[124:127], v24 offset:12304
	ds_read_b128 v[128:131], v24 offset:16400
	s_waitcnt lgkmcnt(5)
	v_fmac_f32_e32 v16, v48, v26
	v_fmac_f32_e32 v17, v48, v30
	v_fmac_f32_e32 v18, v48, v34
	v_fmac_f32_e32 v19, v48, v38
	v_fmac_f32_e32 v23, v48, v42
	v_fmac_f32_e32 v16, v49, v27
	v_fmac_f32_e32 v17, v49, v31
	v_fmac_f32_e32 v18, v49, v35
	v_fmac_f32_e32 v19, v49, v39
	v_fmac_f32_e32 v23, v49, v43
	v_fmac_f32_e32 v16, v50, v28
	v_fmac_f32_e32 v17, v50, v32
	v_fmac_f32_e32 v18, v50, v36
	v_fmac_f32_e32 v19, v50, v40
	v_fmac_f32_e32 v23, v50, v44
	v_fmac_f32_e32 v16, v51, v29
	v_fmac_f32_e32 v17, v51, v33
	v_fmac_f32_e32 v18, v51, v37
	v_fmac_f32_e32 v19, v51, v41
	v_fmac_f32_e32 v23, v51, v45
	ds_read_b128 v[26:29], v24 offset:32
	ds_read_b128 v[30:33], v24 offset:4128
	ds_read_b128 v[34:37], v24 offset:8224
	ds_read_b128 v[38:41], v24 offset:12320
	ds_read_b128 v[42:45], v24 offset:16416
	s_waitcnt lgkmcnt(5)
	v_fmac_f32_e32 v16, v52, v112
	v_fmac_f32_e32 v17, v52, v116
	v_fmac_f32_e32 v18, v52, v120
	v_fmac_f32_e32 v19, v52, v124
	v_fmac_f32_e32 v23, v52, v128
	v_fmac_f32_e32 v16, v53, v113
	v_fmac_f32_e32 v17, v53, v117
	v_fmac_f32_e32 v18, v53, v121
	v_fmac_f32_e32 v19, v53, v125
	v_fmac_f32_e32 v23, v53, v129
	v_fmac_f32_e32 v16, v54, v114
	v_fmac_f32_e32 v17, v54, v118
	v_fmac_f32_e32 v18, v54, v122
	v_fmac_f32_e32 v19, v54, v126
	v_fmac_f32_e32 v23, v54, v130
	v_fmac_f32_e32 v16, v55, v115
	v_fmac_f32_e32 v17, v55, v119
	v_fmac_f32_e32 v18, v55, v123
	v_fmac_f32_e32 v19, v55, v127
	v_fmac_f32_e32 v23, v55, v131
	ds_read_b128 v[112:115], v24 offset:48
	ds_read_b128 v[116:119], v24 offset:4144
	ds_read_b128 v[120:123], v24 offset:8240
	ds_read_b128 v[124:127], v24 offset:12336
	ds_read_b128 v[128:131], v24 offset:16432
	s_waitcnt lgkmcnt(5)
	v_fmac_f32_e32 v16, v56, v26
	v_fmac_f32_e32 v17, v56, v30
	v_fmac_f32_e32 v18, v56, v34
	v_fmac_f32_e32 v19, v56, v38
	v_fmac_f32_e32 v23, v56, v42
	v_fmac_f32_e32 v16, v57, v27
	v_fmac_f32_e32 v17, v57, v31
	v_fmac_f32_e32 v18, v57, v35
	v_fmac_f32_e32 v19, v57, v39
	v_fmac_f32_e32 v23, v57, v43
	v_fmac_f32_e32 v16, v58, v28
	v_fmac_f32_e32 v17, v58, v32
	v_fmac_f32_e32 v18, v58, v36
	v_fmac_f32_e32 v19, v58, v40
	v_fmac_f32_e32 v23, v58, v44
	v_fmac_f32_e32 v16, v59, v29
	v_fmac_f32_e32 v17, v59, v33
	v_fmac_f32_e32 v18, v59, v37
	v_fmac_f32_e32 v19, v59, v41
	v_fmac_f32_e32 v23, v59, v45
	ds_read_b128 v[26:29], v24 offset:64
	ds_read_b128 v[30:33], v24 offset:4160
	ds_read_b128 v[34:37], v24 offset:8256
	ds_read_b128 v[38:41], v24 offset:12352
	ds_read_b128 v[42:45], v24 offset:16448
	s_waitcnt lgkmcnt(5)
	v_fmac_f32_e32 v16, v60, v112
	v_fmac_f32_e32 v17, v60, v116
	v_fmac_f32_e32 v18, v60, v120
	v_fmac_f32_e32 v19, v60, v124
	v_fmac_f32_e32 v23, v60, v128
	v_fmac_f32_e32 v16, v61, v113
	v_fmac_f32_e32 v17, v61, v117
	v_fmac_f32_e32 v18, v61, v121
	v_fmac_f32_e32 v19, v61, v125
	v_fmac_f32_e32 v23, v61, v129
	v_fmac_f32_e32 v16, v62, v114
	v_fmac_f32_e32 v17, v62, v118
	v_fmac_f32_e32 v18, v62, v122
	v_fmac_f32_e32 v19, v62, v126
	v_fmac_f32_e32 v23, v62, v130
	v_fmac_f32_e32 v16, v63, v115
	v_fmac_f32_e32 v17, v63, v119
	v_fmac_f32_e32 v18, v63, v123
	v_fmac_f32_e32 v19, v63, v127
	v_fmac_f32_e32 v23, v63, v131
	global_load_dword v96, v[20:21], off
	v_lshl_add_u64 v[20:21], v[20:21], 0, s[28:29]
	global_load_dword v97, v[20:21], off
	v_lshl_add_u64 v[20:21], v[20:21], 0, s[28:29]
	global_load_dword v98, v[20:21], off
	v_lshl_add_u64 v[20:21], v[20:21], 0, s[28:29]
	global_load_dword v99, v[20:21], off
	v_lshl_add_u64 v[20:21], v[20:21], 0, s[28:29]
	global_load_dword v100, v[20:21], off
	v_lshl_add_u64 v[20:21], v[20:21], 0, s[28:29]
	global_load_dword v101, v[20:21], off
	v_lshl_add_u64 v[20:21], v[20:21], 0, s[28:29]
	global_load_dword v102, v[20:21], off
	v_lshl_add_u64 v[20:21], v[20:21], 0, s[28:29]
	global_load_dword v103, v[20:21], off
	v_lshl_add_u64 v[20:21], v[20:21], 0, s[28:29]
	global_load_dword v104, v[20:21], off
	v_lshl_add_u64 v[20:21], v[20:21], 0, s[28:29]
	global_load_dword v105, v[20:21], off
	v_lshl_add_u64 v[20:21], v[20:21], 0, s[28:29]
	global_load_dword v106, v[20:21], off
	v_lshl_add_u64 v[20:21], v[20:21], 0, s[28:29]
	global_load_dword v107, v[20:21], off
	v_lshl_add_u64 v[20:21], v[20:21], 0, s[28:29]
	global_load_dword v108, v[20:21], off
	v_lshl_add_u64 v[20:21], v[20:21], 0, s[28:29]
	global_load_dword v109, v[20:21], off
	v_lshl_add_u64 v[20:21], v[20:21], 0, s[28:29]
	global_load_dword v110, v[20:21], off
	v_lshl_add_u64 v[20:21], v[20:21], 0, s[28:29]
	global_load_dword v111, v[20:21], off
	v_lshl_add_u64 v[20:21], v[20:21], 0, s[28:29]
	s_waitcnt vmcnt(32)
	ds_read_b128 v[112:115], v24 offset:80
	ds_read_b128 v[116:119], v24 offset:4176
	ds_read_b128 v[120:123], v24 offset:8272
	ds_read_b128 v[124:127], v24 offset:12368
	ds_read_b128 v[128:131], v24 offset:16464
	s_waitcnt lgkmcnt(5)
	v_fmac_f32_e32 v16, v64, v26
	v_fmac_f32_e32 v17, v64, v30
	v_fmac_f32_e32 v18, v64, v34
	v_fmac_f32_e32 v19, v64, v38
	v_fmac_f32_e32 v23, v64, v42
	v_fmac_f32_e32 v16, v65, v27
	v_fmac_f32_e32 v17, v65, v31
	v_fmac_f32_e32 v18, v65, v35
	v_fmac_f32_e32 v19, v65, v39
	v_fmac_f32_e32 v23, v65, v43
	v_fmac_f32_e32 v16, v66, v28
	v_fmac_f32_e32 v17, v66, v32
	v_fmac_f32_e32 v18, v66, v36
	v_fmac_f32_e32 v19, v66, v40
	v_fmac_f32_e32 v23, v66, v44
	v_fmac_f32_e32 v16, v67, v29
	v_fmac_f32_e32 v17, v67, v33
	v_fmac_f32_e32 v18, v67, v37
	v_fmac_f32_e32 v19, v67, v41
	v_fmac_f32_e32 v23, v67, v45
	ds_read_b128 v[26:29], v24 offset:96
	ds_read_b128 v[30:33], v24 offset:4192
	ds_read_b128 v[34:37], v24 offset:8288
	ds_read_b128 v[38:41], v24 offset:12384
	ds_read_b128 v[42:45], v24 offset:16480
	s_waitcnt lgkmcnt(5)
	v_fmac_f32_e32 v16, v68, v112
	v_fmac_f32_e32 v17, v68, v116
	v_fmac_f32_e32 v18, v68, v120
	v_fmac_f32_e32 v19, v68, v124
	v_fmac_f32_e32 v23, v68, v128
	v_fmac_f32_e32 v16, v69, v113
	v_fmac_f32_e32 v17, v69, v117
	v_fmac_f32_e32 v18, v69, v121
	v_fmac_f32_e32 v19, v69, v125
	v_fmac_f32_e32 v23, v69, v129
	v_fmac_f32_e32 v16, v70, v114
	v_fmac_f32_e32 v17, v70, v118
	v_fmac_f32_e32 v18, v70, v122
	v_fmac_f32_e32 v19, v70, v126
	v_fmac_f32_e32 v23, v70, v130
	v_fmac_f32_e32 v16, v71, v115
	v_fmac_f32_e32 v17, v71, v119
	v_fmac_f32_e32 v18, v71, v123
	v_fmac_f32_e32 v19, v71, v127
	v_fmac_f32_e32 v23, v71, v131
	ds_read_b128 v[112:115], v24 offset:112
	ds_read_b128 v[116:119], v24 offset:4208
	ds_read_b128 v[120:123], v24 offset:8304
	ds_read_b128 v[124:127], v24 offset:12400
	ds_read_b128 v[128:131], v24 offset:16496
	s_waitcnt lgkmcnt(5)
	v_fmac_f32_e32 v16, v72, v26
	v_fmac_f32_e32 v17, v72, v30
	v_fmac_f32_e32 v18, v72, v34
	v_fmac_f32_e32 v19, v72, v38
	v_fmac_f32_e32 v23, v72, v42
	v_fmac_f32_e32 v16, v73, v27
	v_fmac_f32_e32 v17, v73, v31
	v_fmac_f32_e32 v18, v73, v35
	v_fmac_f32_e32 v19, v73, v39
	v_fmac_f32_e32 v23, v73, v43
	v_fmac_f32_e32 v16, v74, v28
	v_fmac_f32_e32 v17, v74, v32
	v_fmac_f32_e32 v18, v74, v36
	v_fmac_f32_e32 v19, v74, v40
	v_fmac_f32_e32 v23, v74, v44
	v_fmac_f32_e32 v16, v75, v29
	v_fmac_f32_e32 v17, v75, v33
	v_fmac_f32_e32 v18, v75, v37
	v_fmac_f32_e32 v19, v75, v41
	v_fmac_f32_e32 v23, v75, v45
	ds_read_b128 v[26:29], v24 offset:128
	ds_read_b128 v[30:33], v24 offset:4224
	ds_read_b128 v[34:37], v24 offset:8320
	ds_read_b128 v[38:41], v24 offset:12416
	ds_read_b128 v[42:45], v24 offset:16512
	s_waitcnt lgkmcnt(5)
	v_fmac_f32_e32 v16, v76, v112
	v_fmac_f32_e32 v17, v76, v116
	v_fmac_f32_e32 v18, v76, v120
	v_fmac_f32_e32 v19, v76, v124
	v_fmac_f32_e32 v23, v76, v128
	v_fmac_f32_e32 v16, v77, v113
	v_fmac_f32_e32 v17, v77, v117
	v_fmac_f32_e32 v18, v77, v121
	v_fmac_f32_e32 v19, v77, v125
	v_fmac_f32_e32 v23, v77, v129
	v_fmac_f32_e32 v16, v78, v114
	v_fmac_f32_e32 v17, v78, v118
	v_fmac_f32_e32 v18, v78, v122
	v_fmac_f32_e32 v19, v78, v126
	v_fmac_f32_e32 v23, v78, v130
	v_fmac_f32_e32 v16, v79, v115
	v_fmac_f32_e32 v17, v79, v119
	v_fmac_f32_e32 v18, v79, v123
	v_fmac_f32_e32 v19, v79, v127
	v_fmac_f32_e32 v23, v79, v131
	global_load_dword v48, v[20:21], off
	v_lshl_add_u64 v[20:21], v[20:21], 0, s[28:29]
	global_load_dword v49, v[20:21], off
	v_lshl_add_u64 v[20:21], v[20:21], 0, s[28:29]
	global_load_dword v50, v[20:21], off
	v_lshl_add_u64 v[20:21], v[20:21], 0, s[28:29]
	global_load_dword v51, v[20:21], off
	v_lshl_add_u64 v[20:21], v[20:21], 0, s[28:29]
	global_load_dword v52, v[20:21], off
	v_lshl_add_u64 v[20:21], v[20:21], 0, s[28:29]
	global_load_dword v53, v[20:21], off
	v_lshl_add_u64 v[20:21], v[20:21], 0, s[28:29]
	global_load_dword v54, v[20:21], off
	v_lshl_add_u64 v[20:21], v[20:21], 0, s[28:29]
	global_load_dword v55, v[20:21], off
	v_lshl_add_u64 v[20:21], v[20:21], 0, s[28:29]
	global_load_dword v56, v[20:21], off
	v_lshl_add_u64 v[20:21], v[20:21], 0, s[28:29]
	global_load_dword v57, v[20:21], off
	v_lshl_add_u64 v[20:21], v[20:21], 0, s[28:29]
	global_load_dword v58, v[20:21], off
	v_lshl_add_u64 v[20:21], v[20:21], 0, s[28:29]
	global_load_dword v59, v[20:21], off
	v_lshl_add_u64 v[20:21], v[20:21], 0, s[28:29]
	global_load_dword v60, v[20:21], off
	v_lshl_add_u64 v[20:21], v[20:21], 0, s[28:29]
	global_load_dword v61, v[20:21], off
	v_lshl_add_u64 v[20:21], v[20:21], 0, s[28:29]
	global_load_dword v62, v[20:21], off
	v_lshl_add_u64 v[20:21], v[20:21], 0, s[28:29]
	global_load_dword v63, v[20:21], off
	v_lshl_add_u64 v[20:21], v[20:21], 0, s[28:29]
	s_waitcnt vmcnt(32)
	ds_read_b128 v[112:115], v24 offset:144
	ds_read_b128 v[116:119], v24 offset:4240
	ds_read_b128 v[120:123], v24 offset:8336
	ds_read_b128 v[124:127], v24 offset:12432
	ds_read_b128 v[128:131], v24 offset:16528
	s_waitcnt lgkmcnt(5)
	v_fmac_f32_e32 v16, v80, v26
	v_fmac_f32_e32 v17, v80, v30
	v_fmac_f32_e32 v18, v80, v34
	v_fmac_f32_e32 v19, v80, v38
	v_fmac_f32_e32 v23, v80, v42
	v_fmac_f32_e32 v16, v81, v27
	v_fmac_f32_e32 v17, v81, v31
	v_fmac_f32_e32 v18, v81, v35
	v_fmac_f32_e32 v19, v81, v39
	v_fmac_f32_e32 v23, v81, v43
	v_fmac_f32_e32 v16, v82, v28
	v_fmac_f32_e32 v17, v82, v32
	v_fmac_f32_e32 v18, v82, v36
	v_fmac_f32_e32 v19, v82, v40
	v_fmac_f32_e32 v23, v82, v44
	v_fmac_f32_e32 v16, v83, v29
	v_fmac_f32_e32 v17, v83, v33
	v_fmac_f32_e32 v18, v83, v37
	v_fmac_f32_e32 v19, v83, v41
	v_fmac_f32_e32 v23, v83, v45
	ds_read_b128 v[26:29], v24 offset:160
	ds_read_b128 v[30:33], v24 offset:4256
	ds_read_b128 v[34:37], v24 offset:8352
	ds_read_b128 v[38:41], v24 offset:12448
	ds_read_b128 v[42:45], v24 offset:16544
	s_waitcnt lgkmcnt(5)
	v_fmac_f32_e32 v16, v84, v112
	v_fmac_f32_e32 v17, v84, v116
	v_fmac_f32_e32 v18, v84, v120
	v_fmac_f32_e32 v19, v84, v124
	v_fmac_f32_e32 v23, v84, v128
	v_fmac_f32_e32 v16, v85, v113
	v_fmac_f32_e32 v17, v85, v117
	v_fmac_f32_e32 v18, v85, v121
	v_fmac_f32_e32 v19, v85, v125
	v_fmac_f32_e32 v23, v85, v129
	v_fmac_f32_e32 v16, v86, v114
	v_fmac_f32_e32 v17, v86, v118
	v_fmac_f32_e32 v18, v86, v122
	v_fmac_f32_e32 v19, v86, v126
	v_fmac_f32_e32 v23, v86, v130
	v_fmac_f32_e32 v16, v87, v115
	v_fmac_f32_e32 v17, v87, v119
	v_fmac_f32_e32 v18, v87, v123
	v_fmac_f32_e32 v19, v87, v127
	v_fmac_f32_e32 v23, v87, v131
	ds_read_b128 v[112:115], v24 offset:176
	ds_read_b128 v[116:119], v24 offset:4272
	ds_read_b128 v[120:123], v24 offset:8368
	ds_read_b128 v[124:127], v24 offset:12464
	ds_read_b128 v[128:131], v24 offset:16560
	s_waitcnt lgkmcnt(5)
	v_fmac_f32_e32 v16, v88, v26
	v_fmac_f32_e32 v17, v88, v30
	v_fmac_f32_e32 v18, v88, v34
	v_fmac_f32_e32 v19, v88, v38
	v_fmac_f32_e32 v23, v88, v42
	v_fmac_f32_e32 v16, v89, v27
	v_fmac_f32_e32 v17, v89, v31
	v_fmac_f32_e32 v18, v89, v35
	v_fmac_f32_e32 v19, v89, v39
	v_fmac_f32_e32 v23, v89, v43
	v_fmac_f32_e32 v16, v90, v28
	v_fmac_f32_e32 v17, v90, v32
	v_fmac_f32_e32 v18, v90, v36
	v_fmac_f32_e32 v19, v90, v40
	v_fmac_f32_e32 v23, v90, v44
	v_fmac_f32_e32 v16, v91, v29
	v_fmac_f32_e32 v17, v91, v33
	v_fmac_f32_e32 v18, v91, v37
	v_fmac_f32_e32 v19, v91, v41
	v_fmac_f32_e32 v23, v91, v45
	ds_read_b128 v[26:29], v24 offset:192
	ds_read_b128 v[30:33], v24 offset:4288
	ds_read_b128 v[34:37], v24 offset:8384
	ds_read_b128 v[38:41], v24 offset:12480
	ds_read_b128 v[42:45], v24 offset:16576
	s_waitcnt lgkmcnt(5)
	v_fmac_f32_e32 v16, v92, v112
	v_fmac_f32_e32 v17, v92, v116
	v_fmac_f32_e32 v18, v92, v120
	v_fmac_f32_e32 v19, v92, v124
	v_fmac_f32_e32 v23, v92, v128
	v_fmac_f32_e32 v16, v93, v113
	v_fmac_f32_e32 v17, v93, v117
	v_fmac_f32_e32 v18, v93, v121
	v_fmac_f32_e32 v19, v93, v125
	v_fmac_f32_e32 v23, v93, v129
	v_fmac_f32_e32 v16, v94, v114
	v_fmac_f32_e32 v17, v94, v118
	v_fmac_f32_e32 v18, v94, v122
	v_fmac_f32_e32 v19, v94, v126
	v_fmac_f32_e32 v23, v94, v130
	v_fmac_f32_e32 v16, v95, v115
	v_fmac_f32_e32 v17, v95, v119
	v_fmac_f32_e32 v18, v95, v123
	v_fmac_f32_e32 v19, v95, v127
	v_fmac_f32_e32 v23, v95, v131
	global_load_dword v64, v[20:21], off
	v_lshl_add_u64 v[20:21], v[20:21], 0, s[28:29]
	global_load_dword v65, v[20:21], off
	v_lshl_add_u64 v[20:21], v[20:21], 0, s[28:29]
	global_load_dword v66, v[20:21], off
	v_lshl_add_u64 v[20:21], v[20:21], 0, s[28:29]
	global_load_dword v67, v[20:21], off
	v_lshl_add_u64 v[20:21], v[20:21], 0, s[28:29]
	global_load_dword v68, v[20:21], off
	v_lshl_add_u64 v[20:21], v[20:21], 0, s[28:29]
	global_load_dword v69, v[20:21], off
	v_lshl_add_u64 v[20:21], v[20:21], 0, s[28:29]
	global_load_dword v70, v[20:21], off
	v_lshl_add_u64 v[20:21], v[20:21], 0, s[28:29]
	global_load_dword v71, v[20:21], off
	v_lshl_add_u64 v[20:21], v[20:21], 0, s[28:29]
	global_load_dword v72, v[20:21], off
	v_lshl_add_u64 v[20:21], v[20:21], 0, s[28:29]
	global_load_dword v73, v[20:21], off
	v_lshl_add_u64 v[20:21], v[20:21], 0, s[28:29]
	global_load_dword v74, v[20:21], off
	v_lshl_add_u64 v[20:21], v[20:21], 0, s[28:29]
	global_load_dword v75, v[20:21], off
	v_lshl_add_u64 v[20:21], v[20:21], 0, s[28:29]
	global_load_dword v76, v[20:21], off
	v_lshl_add_u64 v[20:21], v[20:21], 0, s[28:29]
	global_load_dword v77, v[20:21], off
	v_lshl_add_u64 v[20:21], v[20:21], 0, s[28:29]
	global_load_dword v78, v[20:21], off
	v_lshl_add_u64 v[20:21], v[20:21], 0, s[28:29]
	global_load_dword v79, v[20:21], off
	v_lshl_add_u64 v[20:21], v[20:21], 0, s[28:29]
	s_waitcnt vmcnt(32)
	ds_read_b128 v[112:115], v24 offset:208
	ds_read_b128 v[116:119], v24 offset:4304
	ds_read_b128 v[120:123], v24 offset:8400
	ds_read_b128 v[124:127], v24 offset:12496
	ds_read_b128 v[128:131], v24 offset:16592
	s_waitcnt lgkmcnt(5)
	v_fmac_f32_e32 v16, v96, v26
	v_fmac_f32_e32 v17, v96, v30
	v_fmac_f32_e32 v18, v96, v34
	v_fmac_f32_e32 v19, v96, v38
	v_fmac_f32_e32 v23, v96, v42
	v_fmac_f32_e32 v16, v97, v27
	v_fmac_f32_e32 v17, v97, v31
	v_fmac_f32_e32 v18, v97, v35
	v_fmac_f32_e32 v19, v97, v39
	v_fmac_f32_e32 v23, v97, v43
	v_fmac_f32_e32 v16, v98, v28
	v_fmac_f32_e32 v17, v98, v32
	v_fmac_f32_e32 v18, v98, v36
	v_fmac_f32_e32 v19, v98, v40
	v_fmac_f32_e32 v23, v98, v44
	v_fmac_f32_e32 v16, v99, v29
	v_fmac_f32_e32 v17, v99, v33
	v_fmac_f32_e32 v18, v99, v37
	v_fmac_f32_e32 v19, v99, v41
	v_fmac_f32_e32 v23, v99, v45
	ds_read_b128 v[26:29], v24 offset:224
	ds_read_b128 v[30:33], v24 offset:4320
	ds_read_b128 v[34:37], v24 offset:8416
	ds_read_b128 v[38:41], v24 offset:12512
	ds_read_b128 v[42:45], v24 offset:16608
	s_waitcnt lgkmcnt(5)
	v_fmac_f32_e32 v16, v100, v112
	v_fmac_f32_e32 v17, v100, v116
	v_fmac_f32_e32 v18, v100, v120
	v_fmac_f32_e32 v19, v100, v124
	v_fmac_f32_e32 v23, v100, v128
	v_fmac_f32_e32 v16, v101, v113
	v_fmac_f32_e32 v17, v101, v117
	v_fmac_f32_e32 v18, v101, v121
	v_fmac_f32_e32 v19, v101, v125
	v_fmac_f32_e32 v23, v101, v129
	v_fmac_f32_e32 v16, v102, v114
	v_fmac_f32_e32 v17, v102, v118
	v_fmac_f32_e32 v18, v102, v122
	v_fmac_f32_e32 v19, v102, v126
	v_fmac_f32_e32 v23, v102, v130
	v_fmac_f32_e32 v16, v103, v115
	v_fmac_f32_e32 v17, v103, v119
	v_fmac_f32_e32 v18, v103, v123
	v_fmac_f32_e32 v19, v103, v127
	v_fmac_f32_e32 v23, v103, v131
	ds_read_b128 v[112:115], v24 offset:240
	ds_read_b128 v[116:119], v24 offset:4336
	ds_read_b128 v[120:123], v24 offset:8432
	ds_read_b128 v[124:127], v24 offset:12528
	ds_read_b128 v[128:131], v24 offset:16624
	s_waitcnt lgkmcnt(5)
	v_fmac_f32_e32 v16, v104, v26
	v_fmac_f32_e32 v17, v104, v30
	v_fmac_f32_e32 v18, v104, v34
	v_fmac_f32_e32 v19, v104, v38
	v_fmac_f32_e32 v23, v104, v42
	v_fmac_f32_e32 v16, v105, v27
	v_fmac_f32_e32 v17, v105, v31
	v_fmac_f32_e32 v18, v105, v35
	v_fmac_f32_e32 v19, v105, v39
	v_fmac_f32_e32 v23, v105, v43
	v_fmac_f32_e32 v16, v106, v28
	v_fmac_f32_e32 v17, v106, v32
	v_fmac_f32_e32 v18, v106, v36
	v_fmac_f32_e32 v19, v106, v40
	v_fmac_f32_e32 v23, v106, v44
	v_fmac_f32_e32 v16, v107, v29
	v_fmac_f32_e32 v17, v107, v33
	v_fmac_f32_e32 v18, v107, v37
	v_fmac_f32_e32 v19, v107, v41
	v_fmac_f32_e32 v23, v107, v45
	ds_read_b128 v[26:29], v24 offset:256
	ds_read_b128 v[30:33], v24 offset:4352
	ds_read_b128 v[34:37], v24 offset:8448
	ds_read_b128 v[38:41], v24 offset:12544
	ds_read_b128 v[42:45], v24 offset:16640
	s_waitcnt lgkmcnt(5)
	v_fmac_f32_e32 v16, v108, v112
	v_fmac_f32_e32 v17, v108, v116
	v_fmac_f32_e32 v18, v108, v120
	v_fmac_f32_e32 v19, v108, v124
	v_fmac_f32_e32 v23, v108, v128
	v_fmac_f32_e32 v16, v109, v113
	v_fmac_f32_e32 v17, v109, v117
	v_fmac_f32_e32 v18, v109, v121
	v_fmac_f32_e32 v19, v109, v125
	v_fmac_f32_e32 v23, v109, v129
	v_fmac_f32_e32 v16, v110, v114
	v_fmac_f32_e32 v17, v110, v118
	v_fmac_f32_e32 v18, v110, v122
	v_fmac_f32_e32 v19, v110, v126
	v_fmac_f32_e32 v23, v110, v130
	v_fmac_f32_e32 v16, v111, v115
	v_fmac_f32_e32 v17, v111, v119
	v_fmac_f32_e32 v18, v111, v123
	v_fmac_f32_e32 v19, v111, v127
	v_fmac_f32_e32 v23, v111, v131
	global_load_dword v80, v[20:21], off
	v_lshl_add_u64 v[20:21], v[20:21], 0, s[28:29]
	global_load_dword v81, v[20:21], off
	v_lshl_add_u64 v[20:21], v[20:21], 0, s[28:29]
	global_load_dword v82, v[20:21], off
	v_lshl_add_u64 v[20:21], v[20:21], 0, s[28:29]
	global_load_dword v83, v[20:21], off
	v_lshl_add_u64 v[20:21], v[20:21], 0, s[28:29]
	global_load_dword v84, v[20:21], off
	v_lshl_add_u64 v[20:21], v[20:21], 0, s[28:29]
	global_load_dword v85, v[20:21], off
	v_lshl_add_u64 v[20:21], v[20:21], 0, s[28:29]
	global_load_dword v86, v[20:21], off
	v_lshl_add_u64 v[20:21], v[20:21], 0, s[28:29]
	global_load_dword v87, v[20:21], off
	v_lshl_add_u64 v[20:21], v[20:21], 0, s[28:29]
	global_load_dword v88, v[20:21], off
	v_lshl_add_u64 v[20:21], v[20:21], 0, s[28:29]
	global_load_dword v89, v[20:21], off
	v_lshl_add_u64 v[20:21], v[20:21], 0, s[28:29]
	global_load_dword v90, v[20:21], off
	v_lshl_add_u64 v[20:21], v[20:21], 0, s[28:29]
	global_load_dword v91, v[20:21], off
	v_lshl_add_u64 v[20:21], v[20:21], 0, s[28:29]
	global_load_dword v92, v[20:21], off
	v_lshl_add_u64 v[20:21], v[20:21], 0, s[28:29]
	global_load_dword v93, v[20:21], off
	v_lshl_add_u64 v[20:21], v[20:21], 0, s[28:29]
	global_load_dword v94, v[20:21], off
	v_lshl_add_u64 v[20:21], v[20:21], 0, s[28:29]
	global_load_dword v95, v[20:21], off
	v_lshl_add_u64 v[20:21], v[20:21], 0, s[28:29]
	s_waitcnt vmcnt(32)
	ds_read_b128 v[112:115], v24 offset:272
	ds_read_b128 v[116:119], v24 offset:4368
	ds_read_b128 v[120:123], v24 offset:8464
	ds_read_b128 v[124:127], v24 offset:12560
	ds_read_b128 v[128:131], v24 offset:16656
	s_waitcnt lgkmcnt(5)
	v_fmac_f32_e32 v16, v48, v26
	v_fmac_f32_e32 v17, v48, v30
	v_fmac_f32_e32 v18, v48, v34
	v_fmac_f32_e32 v19, v48, v38
	v_fmac_f32_e32 v23, v48, v42
	v_fmac_f32_e32 v16, v49, v27
	v_fmac_f32_e32 v17, v49, v31
	v_fmac_f32_e32 v18, v49, v35
	v_fmac_f32_e32 v19, v49, v39
	v_fmac_f32_e32 v23, v49, v43
	v_fmac_f32_e32 v16, v50, v28
	v_fmac_f32_e32 v17, v50, v32
	v_fmac_f32_e32 v18, v50, v36
	v_fmac_f32_e32 v19, v50, v40
	v_fmac_f32_e32 v23, v50, v44
	v_fmac_f32_e32 v16, v51, v29
	v_fmac_f32_e32 v17, v51, v33
	v_fmac_f32_e32 v18, v51, v37
	v_fmac_f32_e32 v19, v51, v41
	v_fmac_f32_e32 v23, v51, v45
	ds_read_b128 v[26:29], v24 offset:288
	ds_read_b128 v[30:33], v24 offset:4384
	ds_read_b128 v[34:37], v24 offset:8480
	ds_read_b128 v[38:41], v24 offset:12576
	ds_read_b128 v[42:45], v24 offset:16672
	s_waitcnt lgkmcnt(5)
	v_fmac_f32_e32 v16, v52, v112
	v_fmac_f32_e32 v17, v52, v116
	v_fmac_f32_e32 v18, v52, v120
	v_fmac_f32_e32 v19, v52, v124
	v_fmac_f32_e32 v23, v52, v128
	v_fmac_f32_e32 v16, v53, v113
	v_fmac_f32_e32 v17, v53, v117
	v_fmac_f32_e32 v18, v53, v121
	v_fmac_f32_e32 v19, v53, v125
	v_fmac_f32_e32 v23, v53, v129
	v_fmac_f32_e32 v16, v54, v114
	v_fmac_f32_e32 v17, v54, v118
	v_fmac_f32_e32 v18, v54, v122
	v_fmac_f32_e32 v19, v54, v126
	v_fmac_f32_e32 v23, v54, v130
	v_fmac_f32_e32 v16, v55, v115
	v_fmac_f32_e32 v17, v55, v119
	v_fmac_f32_e32 v18, v55, v123
	v_fmac_f32_e32 v19, v55, v127
	v_fmac_f32_e32 v23, v55, v131
	ds_read_b128 v[112:115], v24 offset:304
	ds_read_b128 v[116:119], v24 offset:4400
	ds_read_b128 v[120:123], v24 offset:8496
	ds_read_b128 v[124:127], v24 offset:12592
	ds_read_b128 v[128:131], v24 offset:16688
	s_waitcnt lgkmcnt(5)
	v_fmac_f32_e32 v16, v56, v26
	v_fmac_f32_e32 v17, v56, v30
	v_fmac_f32_e32 v18, v56, v34
	v_fmac_f32_e32 v19, v56, v38
	v_fmac_f32_e32 v23, v56, v42
	v_fmac_f32_e32 v16, v57, v27
	v_fmac_f32_e32 v17, v57, v31
	v_fmac_f32_e32 v18, v57, v35
	v_fmac_f32_e32 v19, v57, v39
	v_fmac_f32_e32 v23, v57, v43
	v_fmac_f32_e32 v16, v58, v28
	v_fmac_f32_e32 v17, v58, v32
	v_fmac_f32_e32 v18, v58, v36
	v_fmac_f32_e32 v19, v58, v40
	v_fmac_f32_e32 v23, v58, v44
	v_fmac_f32_e32 v16, v59, v29
	v_fmac_f32_e32 v17, v59, v33
	v_fmac_f32_e32 v18, v59, v37
	v_fmac_f32_e32 v19, v59, v41
	v_fmac_f32_e32 v23, v59, v45
	ds_read_b128 v[26:29], v24 offset:320
	ds_read_b128 v[30:33], v24 offset:4416
	ds_read_b128 v[34:37], v24 offset:8512
	ds_read_b128 v[38:41], v24 offset:12608
	ds_read_b128 v[42:45], v24 offset:16704
	s_waitcnt lgkmcnt(5)
	v_fmac_f32_e32 v16, v60, v112
	v_fmac_f32_e32 v17, v60, v116
	v_fmac_f32_e32 v18, v60, v120
	v_fmac_f32_e32 v19, v60, v124
	v_fmac_f32_e32 v23, v60, v128
	v_fmac_f32_e32 v16, v61, v113
	v_fmac_f32_e32 v17, v61, v117
	v_fmac_f32_e32 v18, v61, v121
	v_fmac_f32_e32 v19, v61, v125
	v_fmac_f32_e32 v23, v61, v129
	v_fmac_f32_e32 v16, v62, v114
	v_fmac_f32_e32 v17, v62, v118
	v_fmac_f32_e32 v18, v62, v122
	v_fmac_f32_e32 v19, v62, v126
	v_fmac_f32_e32 v23, v62, v130
	v_fmac_f32_e32 v16, v63, v115
	v_fmac_f32_e32 v17, v63, v119
	v_fmac_f32_e32 v18, v63, v123
	v_fmac_f32_e32 v19, v63, v127
	v_fmac_f32_e32 v23, v63, v131
	global_load_dword v96, v[20:21], off
	v_lshl_add_u64 v[20:21], v[20:21], 0, s[28:29]
	global_load_dword v97, v[20:21], off
	v_lshl_add_u64 v[20:21], v[20:21], 0, s[28:29]
	global_load_dword v98, v[20:21], off
	v_lshl_add_u64 v[20:21], v[20:21], 0, s[28:29]
	global_load_dword v99, v[20:21], off
	v_lshl_add_u64 v[20:21], v[20:21], 0, s[28:29]
	global_load_dword v100, v[20:21], off
	v_lshl_add_u64 v[20:21], v[20:21], 0, s[28:29]
	global_load_dword v101, v[20:21], off
	v_lshl_add_u64 v[20:21], v[20:21], 0, s[28:29]
	global_load_dword v102, v[20:21], off
	v_lshl_add_u64 v[20:21], v[20:21], 0, s[28:29]
	global_load_dword v103, v[20:21], off
	v_lshl_add_u64 v[20:21], v[20:21], 0, s[28:29]
	global_load_dword v104, v[20:21], off
	v_lshl_add_u64 v[20:21], v[20:21], 0, s[28:29]
	global_load_dword v105, v[20:21], off
	v_lshl_add_u64 v[20:21], v[20:21], 0, s[28:29]
	global_load_dword v106, v[20:21], off
	v_lshl_add_u64 v[20:21], v[20:21], 0, s[28:29]
	global_load_dword v107, v[20:21], off
	v_lshl_add_u64 v[20:21], v[20:21], 0, s[28:29]
	global_load_dword v108, v[20:21], off
	v_lshl_add_u64 v[20:21], v[20:21], 0, s[28:29]
	global_load_dword v109, v[20:21], off
	v_lshl_add_u64 v[20:21], v[20:21], 0, s[28:29]
	global_load_dword v110, v[20:21], off
	v_lshl_add_u64 v[20:21], v[20:21], 0, s[28:29]
	global_load_dword v111, v[20:21], off
	v_lshl_add_u64 v[20:21], v[20:21], 0, s[28:29]
	s_waitcnt vmcnt(32)
	ds_read_b128 v[112:115], v24 offset:336
	ds_read_b128 v[116:119], v24 offset:4432
	ds_read_b128 v[120:123], v24 offset:8528
	ds_read_b128 v[124:127], v24 offset:12624
	ds_read_b128 v[128:131], v24 offset:16720
	s_waitcnt lgkmcnt(5)
	v_fmac_f32_e32 v16, v64, v26
	v_fmac_f32_e32 v17, v64, v30
	v_fmac_f32_e32 v18, v64, v34
	v_fmac_f32_e32 v19, v64, v38
	v_fmac_f32_e32 v23, v64, v42
	v_fmac_f32_e32 v16, v65, v27
	v_fmac_f32_e32 v17, v65, v31
	v_fmac_f32_e32 v18, v65, v35
	v_fmac_f32_e32 v19, v65, v39
	v_fmac_f32_e32 v23, v65, v43
	v_fmac_f32_e32 v16, v66, v28
	v_fmac_f32_e32 v17, v66, v32
	v_fmac_f32_e32 v18, v66, v36
	v_fmac_f32_e32 v19, v66, v40
	v_fmac_f32_e32 v23, v66, v44
	v_fmac_f32_e32 v16, v67, v29
	v_fmac_f32_e32 v17, v67, v33
	v_fmac_f32_e32 v18, v67, v37
	v_fmac_f32_e32 v19, v67, v41
	v_fmac_f32_e32 v23, v67, v45
	ds_read_b128 v[26:29], v24 offset:352
	ds_read_b128 v[30:33], v24 offset:4448
	ds_read_b128 v[34:37], v24 offset:8544
	ds_read_b128 v[38:41], v24 offset:12640
	ds_read_b128 v[42:45], v24 offset:16736
	s_waitcnt lgkmcnt(5)
	v_fmac_f32_e32 v16, v68, v112
	v_fmac_f32_e32 v17, v68, v116
	v_fmac_f32_e32 v18, v68, v120
	v_fmac_f32_e32 v19, v68, v124
	v_fmac_f32_e32 v23, v68, v128
	v_fmac_f32_e32 v16, v69, v113
	v_fmac_f32_e32 v17, v69, v117
	v_fmac_f32_e32 v18, v69, v121
	v_fmac_f32_e32 v19, v69, v125
	v_fmac_f32_e32 v23, v69, v129
	v_fmac_f32_e32 v16, v70, v114
	v_fmac_f32_e32 v17, v70, v118
	v_fmac_f32_e32 v18, v70, v122
	v_fmac_f32_e32 v19, v70, v126
	v_fmac_f32_e32 v23, v70, v130
	v_fmac_f32_e32 v16, v71, v115
	v_fmac_f32_e32 v17, v71, v119
	v_fmac_f32_e32 v18, v71, v123
	v_fmac_f32_e32 v19, v71, v127
	v_fmac_f32_e32 v23, v71, v131
	ds_read_b128 v[112:115], v24 offset:368
	ds_read_b128 v[116:119], v24 offset:4464
	ds_read_b128 v[120:123], v24 offset:8560
	ds_read_b128 v[124:127], v24 offset:12656
	ds_read_b128 v[128:131], v24 offset:16752
	s_waitcnt lgkmcnt(5)
	v_fmac_f32_e32 v16, v72, v26
	v_fmac_f32_e32 v17, v72, v30
	v_fmac_f32_e32 v18, v72, v34
	v_fmac_f32_e32 v19, v72, v38
	v_fmac_f32_e32 v23, v72, v42
	v_fmac_f32_e32 v16, v73, v27
	v_fmac_f32_e32 v17, v73, v31
	v_fmac_f32_e32 v18, v73, v35
	v_fmac_f32_e32 v19, v73, v39
	v_fmac_f32_e32 v23, v73, v43
	v_fmac_f32_e32 v16, v74, v28
	v_fmac_f32_e32 v17, v74, v32
	v_fmac_f32_e32 v18, v74, v36
	v_fmac_f32_e32 v19, v74, v40
	v_fmac_f32_e32 v23, v74, v44
	v_fmac_f32_e32 v16, v75, v29
	v_fmac_f32_e32 v17, v75, v33
	v_fmac_f32_e32 v18, v75, v37
	v_fmac_f32_e32 v19, v75, v41
	v_fmac_f32_e32 v23, v75, v45
	ds_read_b128 v[26:29], v24 offset:384
	ds_read_b128 v[30:33], v24 offset:4480
	ds_read_b128 v[34:37], v24 offset:8576
	ds_read_b128 v[38:41], v24 offset:12672
	ds_read_b128 v[42:45], v24 offset:16768
	s_waitcnt lgkmcnt(5)
	v_fmac_f32_e32 v16, v76, v112
	v_fmac_f32_e32 v17, v76, v116
	v_fmac_f32_e32 v18, v76, v120
	v_fmac_f32_e32 v19, v76, v124
	v_fmac_f32_e32 v23, v76, v128
	v_fmac_f32_e32 v16, v77, v113
	v_fmac_f32_e32 v17, v77, v117
	v_fmac_f32_e32 v18, v77, v121
	v_fmac_f32_e32 v19, v77, v125
	v_fmac_f32_e32 v23, v77, v129
	v_fmac_f32_e32 v16, v78, v114
	v_fmac_f32_e32 v17, v78, v118
	v_fmac_f32_e32 v18, v78, v122
	v_fmac_f32_e32 v19, v78, v126
	v_fmac_f32_e32 v23, v78, v130
	v_fmac_f32_e32 v16, v79, v115
	v_fmac_f32_e32 v17, v79, v119
	v_fmac_f32_e32 v18, v79, v123
	v_fmac_f32_e32 v19, v79, v127
	v_fmac_f32_e32 v23, v79, v131
	s_waitcnt vmcnt(16)
	ds_read_b128 v[112:115], v24 offset:400
	ds_read_b128 v[116:119], v24 offset:4496
	ds_read_b128 v[120:123], v24 offset:8592
	ds_read_b128 v[124:127], v24 offset:12688
	ds_read_b128 v[128:131], v24 offset:16784
	s_waitcnt lgkmcnt(5)
	v_fmac_f32_e32 v16, v80, v26
	v_fmac_f32_e32 v17, v80, v30
	v_fmac_f32_e32 v18, v80, v34
	v_fmac_f32_e32 v19, v80, v38
	v_fmac_f32_e32 v23, v80, v42
	v_fmac_f32_e32 v16, v81, v27
	v_fmac_f32_e32 v17, v81, v31
	v_fmac_f32_e32 v18, v81, v35
	v_fmac_f32_e32 v19, v81, v39
	v_fmac_f32_e32 v23, v81, v43
	v_fmac_f32_e32 v16, v82, v28
	v_fmac_f32_e32 v17, v82, v32
	v_fmac_f32_e32 v18, v82, v36
	v_fmac_f32_e32 v19, v82, v40
	v_fmac_f32_e32 v23, v82, v44
	v_fmac_f32_e32 v16, v83, v29
	v_fmac_f32_e32 v17, v83, v33
	v_fmac_f32_e32 v18, v83, v37
	v_fmac_f32_e32 v19, v83, v41
	v_fmac_f32_e32 v23, v83, v45
	ds_read_b128 v[26:29], v24 offset:416
	ds_read_b128 v[30:33], v24 offset:4512
	ds_read_b128 v[34:37], v24 offset:8608
	ds_read_b128 v[38:41], v24 offset:12704
	ds_read_b128 v[42:45], v24 offset:16800
	s_waitcnt lgkmcnt(5)
	v_fmac_f32_e32 v16, v84, v112
	v_fmac_f32_e32 v17, v84, v116
	v_fmac_f32_e32 v18, v84, v120
	v_fmac_f32_e32 v19, v84, v124
	v_fmac_f32_e32 v23, v84, v128
	v_fmac_f32_e32 v16, v85, v113
	v_fmac_f32_e32 v17, v85, v117
	v_fmac_f32_e32 v18, v85, v121
	v_fmac_f32_e32 v19, v85, v125
	v_fmac_f32_e32 v23, v85, v129
	v_fmac_f32_e32 v16, v86, v114
	v_fmac_f32_e32 v17, v86, v118
	v_fmac_f32_e32 v18, v86, v122
	v_fmac_f32_e32 v19, v86, v126
	v_fmac_f32_e32 v23, v86, v130
	v_fmac_f32_e32 v16, v87, v115
	v_fmac_f32_e32 v17, v87, v119
	v_fmac_f32_e32 v18, v87, v123
	v_fmac_f32_e32 v19, v87, v127
	v_fmac_f32_e32 v23, v87, v131
	ds_read_b128 v[112:115], v24 offset:432
	ds_read_b128 v[116:119], v24 offset:4528
	ds_read_b128 v[120:123], v24 offset:8624
	ds_read_b128 v[124:127], v24 offset:12720
	ds_read_b128 v[128:131], v24 offset:16816
	s_waitcnt lgkmcnt(5)
	v_fmac_f32_e32 v16, v88, v26
	v_fmac_f32_e32 v17, v88, v30
	v_fmac_f32_e32 v18, v88, v34
	v_fmac_f32_e32 v19, v88, v38
	v_fmac_f32_e32 v23, v88, v42
	v_fmac_f32_e32 v16, v89, v27
	v_fmac_f32_e32 v17, v89, v31
	v_fmac_f32_e32 v18, v89, v35
	v_fmac_f32_e32 v19, v89, v39
	v_fmac_f32_e32 v23, v89, v43
	v_fmac_f32_e32 v16, v90, v28
	v_fmac_f32_e32 v17, v90, v32
	v_fmac_f32_e32 v18, v90, v36
	v_fmac_f32_e32 v19, v90, v40
	v_fmac_f32_e32 v23, v90, v44
	v_fmac_f32_e32 v16, v91, v29
	v_fmac_f32_e32 v17, v91, v33
	v_fmac_f32_e32 v18, v91, v37
	v_fmac_f32_e32 v19, v91, v41
	v_fmac_f32_e32 v23, v91, v45
	ds_read_b128 v[26:29], v24 offset:448
	ds_read_b128 v[30:33], v24 offset:4544
	ds_read_b128 v[34:37], v24 offset:8640
	ds_read_b128 v[38:41], v24 offset:12736
	ds_read_b128 v[42:45], v24 offset:16832
	s_waitcnt lgkmcnt(5)
	v_fmac_f32_e32 v16, v92, v112
	v_fmac_f32_e32 v17, v92, v116
	v_fmac_f32_e32 v18, v92, v120
	v_fmac_f32_e32 v19, v92, v124
	v_fmac_f32_e32 v23, v92, v128
	v_fmac_f32_e32 v16, v93, v113
	v_fmac_f32_e32 v17, v93, v117
	v_fmac_f32_e32 v18, v93, v121
	v_fmac_f32_e32 v19, v93, v125
	v_fmac_f32_e32 v23, v93, v129
	v_fmac_f32_e32 v16, v94, v114
	v_fmac_f32_e32 v17, v94, v118
	v_fmac_f32_e32 v18, v94, v122
	v_fmac_f32_e32 v19, v94, v126
	v_fmac_f32_e32 v23, v94, v130
	v_fmac_f32_e32 v16, v95, v115
	v_fmac_f32_e32 v17, v95, v119
	v_fmac_f32_e32 v18, v95, v123
	v_fmac_f32_e32 v19, v95, v127
	v_fmac_f32_e32 v23, v95, v131
	s_waitcnt vmcnt(0)
	ds_read_b128 v[112:115], v24 offset:464
	ds_read_b128 v[116:119], v24 offset:4560
	ds_read_b128 v[120:123], v24 offset:8656
	ds_read_b128 v[124:127], v24 offset:12752
	ds_read_b128 v[128:131], v24 offset:16848
	s_waitcnt lgkmcnt(5)
	v_fmac_f32_e32 v16, v96, v26
	v_fmac_f32_e32 v17, v96, v30
	v_fmac_f32_e32 v18, v96, v34
	v_fmac_f32_e32 v19, v96, v38
	v_fmac_f32_e32 v23, v96, v42
	v_fmac_f32_e32 v16, v97, v27
	v_fmac_f32_e32 v17, v97, v31
	v_fmac_f32_e32 v18, v97, v35
	v_fmac_f32_e32 v19, v97, v39
	v_fmac_f32_e32 v23, v97, v43
	v_fmac_f32_e32 v16, v98, v28
	v_fmac_f32_e32 v17, v98, v32
	v_fmac_f32_e32 v18, v98, v36
	v_fmac_f32_e32 v19, v98, v40
	v_fmac_f32_e32 v23, v98, v44
	v_fmac_f32_e32 v16, v99, v29
	v_fmac_f32_e32 v17, v99, v33
	v_fmac_f32_e32 v18, v99, v37
	v_fmac_f32_e32 v19, v99, v41
	v_fmac_f32_e32 v23, v99, v45
	ds_read_b128 v[26:29], v24 offset:480
	ds_read_b128 v[30:33], v24 offset:4576
	ds_read_b128 v[34:37], v24 offset:8672
	ds_read_b128 v[38:41], v24 offset:12768
	ds_read_b128 v[42:45], v24 offset:16864
	s_waitcnt lgkmcnt(5)
	v_fmac_f32_e32 v16, v100, v112
	v_fmac_f32_e32 v17, v100, v116
	v_fmac_f32_e32 v18, v100, v120
	v_fmac_f32_e32 v19, v100, v124
	v_fmac_f32_e32 v23, v100, v128
	v_fmac_f32_e32 v16, v101, v113
	v_fmac_f32_e32 v17, v101, v117
	v_fmac_f32_e32 v18, v101, v121
	v_fmac_f32_e32 v19, v101, v125
	v_fmac_f32_e32 v23, v101, v129
	v_fmac_f32_e32 v16, v102, v114
	v_fmac_f32_e32 v17, v102, v118
	v_fmac_f32_e32 v18, v102, v122
	v_fmac_f32_e32 v19, v102, v126
	v_fmac_f32_e32 v23, v102, v130
	v_fmac_f32_e32 v16, v103, v115
	v_fmac_f32_e32 v17, v103, v119
	v_fmac_f32_e32 v18, v103, v123
	v_fmac_f32_e32 v19, v103, v127
	v_fmac_f32_e32 v23, v103, v131
	ds_read_b128 v[112:115], v24 offset:496
	ds_read_b128 v[116:119], v24 offset:4592
	ds_read_b128 v[120:123], v24 offset:8688
	ds_read_b128 v[124:127], v24 offset:12784
	ds_read_b128 v[128:131], v24 offset:16880
	s_waitcnt lgkmcnt(5)
	v_fmac_f32_e32 v16, v104, v26
	v_fmac_f32_e32 v17, v104, v30
	v_fmac_f32_e32 v18, v104, v34
	v_fmac_f32_e32 v19, v104, v38
	v_fmac_f32_e32 v23, v104, v42
	v_fmac_f32_e32 v16, v105, v27
	v_fmac_f32_e32 v17, v105, v31
	v_fmac_f32_e32 v18, v105, v35
	v_fmac_f32_e32 v19, v105, v39
	v_fmac_f32_e32 v23, v105, v43
	v_fmac_f32_e32 v16, v106, v28
	v_fmac_f32_e32 v17, v106, v32
	v_fmac_f32_e32 v18, v106, v36
	v_fmac_f32_e32 v19, v106, v40
	v_fmac_f32_e32 v23, v106, v44
	v_fmac_f32_e32 v16, v107, v29
	v_fmac_f32_e32 v17, v107, v33
	v_fmac_f32_e32 v18, v107, v37
	v_fmac_f32_e32 v19, v107, v41
	v_fmac_f32_e32 v23, v107, v45
	s_waitcnt lgkmcnt(0)
	v_fmac_f32_e32 v16, v108, v112
	v_fmac_f32_e32 v17, v108, v116
	v_fmac_f32_e32 v18, v108, v120
	v_fmac_f32_e32 v19, v108, v124
	v_fmac_f32_e32 v23, v108, v128
	v_fmac_f32_e32 v16, v109, v113
	v_fmac_f32_e32 v17, v109, v117
	v_fmac_f32_e32 v18, v109, v121
	v_fmac_f32_e32 v19, v109, v125
	v_fmac_f32_e32 v23, v109, v129
	v_fmac_f32_e32 v16, v110, v114
	v_fmac_f32_e32 v17, v110, v118
	v_fmac_f32_e32 v18, v110, v122
	v_fmac_f32_e32 v19, v110, v126
	v_fmac_f32_e32 v23, v110, v130
	v_fmac_f32_e32 v16, v111, v115
	v_fmac_f32_e32 v17, v111, v119
	v_fmac_f32_e32 v18, v111, v123
	v_fmac_f32_e32 v19, v111, v127
	v_fmac_f32_e32 v23, v111, v131
	s_movk_i32 s8, 0x280
	v_mul_lo_u32 v2, v22, s8
	v_lshl_or_b32 v0, v0, 2, v2
	v_add_u32_e32 v2, 0x5000, v0
	v_mov_b32_e32 v4, v151
	s_movk_i32 s8, 0xa0
	ds_write2_b32 v2, v16, v17 offset1:32
	ds_write2_b32 v2, v18, v19 offset0:64 offset1:96
	ds_write_b32 v0, v23 offset:20992
	s_waitcnt lgkmcnt(0)
	s_barrier
	s_nop 0
	v_cmp_gt_i32_e32 vcc, s8, v4
	s_and_saveexec_b64 s[28:29], vcc
	v_readlane_b32 s12, v253, 4
	v_readlane_b32 s13, v253, 5
	s_movk_i32 s14, 0xc00
	s_cbranch_execz .LBB0_827
	s_and_b64 s[8:9], s[0:1], exec
	s_cselect_b32 s8, 0xc00, 0
	s_add_i32 s9, s50, s8
	v_and_b32_e32 v6, 31, v4
	v_readlane_b32 s52, v252, 29
	s_and_b64 s[0:1], s[0:1], exec
	v_or_b32_e32 v0, s9, v6
	v_readlane_b32 s54, v252, 31
	v_readlane_b32 s55, v252, 32
	s_cselect_b32 s8, 5, 0
	v_lshlrev_b32_e32 v5, 2, v6
	v_lshl_add_u64 v[2:3], v[0:1], 2, s[54:55]
	v_or_b32_e32 v0, s50, v6
	s_mov_b64 s[0:1], 0
	v_readlane_b32 s53, v252, 30
	v_readlane_b32 s56, v252, 33
	v_readlane_b32 s57, v252, 34
	v_readlane_b32 s58, v252, 35
	v_readlane_b32 s59, v252, 36
	v_readlane_b32 s60, v252, 37
	v_readlane_b32 s61, v252, 38
	v_readlane_b32 s62, v252, 39
	v_readlane_b32 s63, v252, 40
	v_readlane_b32 s64, v252, 41
	v_readlane_b32 s65, v252, 42
	v_readlane_b32 s66, v252, 43
	v_readlane_b32 s67, v252, 44

.LBB0_849:
	v_add_u32_e32 v0, s8, v37
	ds_read2_b32 v[88:89], v0 offset1:1
	ds_read2_b32 v[90:91], v0 offset0:2 offset1:3
	ds_read2_b32 v[92:93], v0 offset0:4 offset1:5
	ds_read2_b32 v[94:95], v0 offset0:6 offset1:7
	ds_read2_b32 v[96:97], v0 offset0:8 offset1:9
	ds_read2_b32 v[98:99], v0 offset0:10 offset1:11
	ds_read2_b32 v[100:101], v0 offset0:12 offset1:13
	ds_read2_b32 v[102:103], v0 offset0:14 offset1:15
	ds_read2_b32 v[104:105], v0 offset0:16 offset1:17
	ds_read2_b32 v[106:107], v0 offset0:18 offset1:19
	ds_read2_b32 v[108:109], v0 offset0:20 offset1:21
	ds_read_b32 v110, v0 offset:88
	s_waitcnt vmcnt(1) lgkmcnt(11)
	ds_read2_b32 v[112:113], v0 offset0:23 offset1:24
	v_fma_f32 v59, v3, v88, v56
	v_fmac_f32_e32 v59, v7, v89
	s_waitcnt lgkmcnt(11)
	ds_read2_b32 v[114:115], v0 offset0:25 offset1:26
	v_fmac_f32_e32 v59, v9, v90
	v_fmac_f32_e32 v59, v11, v91
	s_waitcnt lgkmcnt(11)
	ds_read2_b32 v[116:117], v0 offset0:27 offset1:28
	v_fmac_f32_e32 v59, v13, v92
	v_fmac_f32_e32 v59, v15, v93
	s_waitcnt lgkmcnt(11)
	ds_read2_b32 v[118:119], v0 offset0:29 offset1:30
	v_fmac_f32_e32 v59, v17, v94
	v_fmac_f32_e32 v59, v19, v95
	s_waitcnt lgkmcnt(11)
	ds_read2_b32 v[120:121], v0 offset0:31 offset1:32
	v_fmac_f32_e32 v59, v21, v96
	v_fmac_f32_e32 v59, v23, v97
	s_waitcnt lgkmcnt(11)
	v_fmac_f32_e32 v59, v25, v98
	v_fmac_f32_e32 v59, v27, v99
	s_waitcnt lgkmcnt(10)
	v_fmac_f32_e32 v59, v29, v100
	v_fmac_f32_e32 v59, v31, v101
	s_waitcnt lgkmcnt(9)
	v_fmac_f32_e32 v59, v33, v102
	v_fmac_f32_e32 v59, v35, v103
	s_waitcnt lgkmcnt(8)
	v_fmac_f32_e32 v59, v39, v104
	v_fmac_f32_e32 v59, v50, v105
	s_waitcnt lgkmcnt(7)
	v_fmac_f32_e32 v59, v51, v106
	v_fmac_f32_e32 v59, v52, v107
	s_waitcnt lgkmcnt(6)
	v_fmac_f32_e32 v59, v53, v108
	v_fmac_f32_e32 v59, v54, v109
	s_waitcnt lgkmcnt(5)
	v_fmac_f32_e32 v59, v55, v110
	s_waitcnt lgkmcnt(4)
	v_pk_mul_f32 v[112:113], v[40:41], v[112:113]
	s_nop 0
	v_add_f32_e32 v59, v59, v112
	v_add_f32_e32 v59, v59, v113
	s_waitcnt lgkmcnt(3)
	v_pk_mul_f32 v[114:115], v[42:43], v[114:115]
	s_nop 0
	v_add_f32_e32 v59, v59, v114
	v_add_f32_e32 v59, v59, v115
	s_waitcnt lgkmcnt(2)
	v_pk_mul_f32 v[116:117], v[44:45], v[116:117]
	s_nop 0
	v_add_f32_e32 v59, v59, v116
	v_add_f32_e32 v59, v59, v117
	s_waitcnt lgkmcnt(1)
	v_pk_mul_f32 v[118:119], v[46:47], v[118:119]
	s_nop 0
	v_add_f32_e32 v59, v59, v118
	v_add_f32_e32 v59, v59, v119
	s_waitcnt lgkmcnt(0)
	v_pk_mul_f32 v[120:121], v[48:49], v[120:121]
	s_nop 0
	v_add_f32_e32 v0, v59, v120
	v_add_f32_e32 v0, v0, v121
	s_waitcnt vmcnt(0)
	v_mul_f32_e32 v59, v57, v0
	v_and_b32_e32 v60, 0x7fffffff, v59
	v_cmp_nlt_f32_e64 s[0:1], |v59|, s3
	s_and_saveexec_b64 s[10:11], s[0:1]
	s_xor_b64 s[48:49], exec, s[10:11]
	s_cbranch_execz .LBB0_851
	v_lshrrev_b32_e32 v0, 23, v60
	v_add_u32_e32 v0, 0xffffff88, v0
	v_cmp_lt_u32_e32 vcc, 63, v0
	s_mov_b32 s9, 0x3c439041
	s_nop 0
	v_cndmask_b32_e32 v61, 0, v213, vcc
	v_add_u32_e32 v0, v61, v0
	v_cmp_lt_u32_e64 s[0:1], 31, v0
	s_nop 1
	v_cndmask_b32_e64 v61, 0, v214, s[0:1]
	v_add_u32_e32 v0, v61, v0
	v_cmp_lt_u32_e64 s[40:41], 31, v0
	s_nop 1
	v_cndmask_b32_e64 v61, 0, v214, s[40:41]
	v_add_u32_e32 v61, v61, v0
	v_and_b32_e32 v0, 0x7fffff, v60
	v_or_b32_e32 v65, 0x800000, v0
	v_mad_u64_u32 v[62:63], s[10:11], v65, s36, 0
	v_mov_b32_e32 v0, v63
	v_mad_u64_u32 v[68:69], s[10:11], v65, s9, v[0:1]
	v_mov_b32_e32 v0, v69
	v_mad_u64_u32 v[70:71], s[10:11], v65, s37, v[0:1]
	v_mov_b32_e32 v0, v71
	s_mov_b32 s9, 0xf534ddc0
	v_mad_u64_u32 v[72:73], s[10:11], v65, s9, v[0:1]
	v_mov_b32_e32 v0, v73
	v_mad_u64_u32 v[74:75], s[10:11], v65, s72, v[0:1]
	v_mov_b32_e32 v0, v75
	v_mad_u64_u32 v[76:77], s[10:11], v65, s69, v[0:1]
	v_mov_b32_e32 v0, v77
	v_mad_u64_u32 v[78:79], s[10:11], v65, s97, v[0:1]
	v_cndmask_b32_e32 v63, v76, v72, vcc
	v_cndmask_b32_e32 v0, v78, v74, vcc
	v_cndmask_b32_e32 v66, v79, v76, vcc
	v_cndmask_b32_e64 v65, v0, v63, s[0:1]
	v_cndmask_b32_e64 v0, v66, v0, s[0:1]
	v_cndmask_b32_e32 v66, v74, v70, vcc
	v_cndmask_b32_e64 v63, v63, v66, s[0:1]
	v_sub_u32_e32 v69, 32, v61
	v_cmp_eq_u32_e64 s[42:43], 0, v61
	v_cndmask_b32_e32 v61, v72, v68, vcc
	v_cndmask_b32_e64 v0, v0, v65, s[40:41]
	v_cndmask_b32_e64 v65, v65, v63, s[40:41]
	v_cndmask_b32_e64 v66, v66, v61, s[0:1]
	v_alignbit_b32 v71, v0, v65, v69
	v_cndmask_b32_e64 v63, v63, v66, s[40:41]
	v_cndmask_b32_e32 v62, v70, v62, vcc
	v_cndmask_b32_e64 v0, v71, v0, s[42:43]
	v_alignbit_b32 v68, v65, v63, v69
	v_cndmask_b32_e64 v61, v61, v62, s[0:1]
	v_cndmask_b32_e64 v65, v68, v65, s[42:43]
	v_bfe_u32 v72, v0, 29, 1
	v_cndmask_b32_e64 v61, v66, v61, s[40:41]
	v_alignbit_b32 v68, v0, v65, 30
	v_sub_u32_e32 v73, 0, v72
	v_alignbit_b32 v62, v63, v61, v69
	v_xor_b32_e32 v68, v68, v73
	v_cndmask_b32_e64 v62, v62, v63, s[42:43]
	v_alignbit_b32 v63, v65, v62, 30
	v_ffbh_u32_e32 v65, v68
	v_min_u32_e32 v65, 32, v65
	v_alignbit_b32 v61, v62, v61, 30
	v_xor_b32_e32 v63, v63, v73
	v_sub_u32_e32 v66, 31, v65
	v_xor_b32_e32 v61, v61, v73
	v_alignbit_b32 v68, v68, v63, v66
	v_alignbit_b32 v61, v63, v61, v66
	v_alignbit_b32 v62, v68, v61, 9
	v_ffbh_u32_e32 v63, v62
	v_min_u32_e32 v63, 32, v63
	v_lshrrev_b32_e32 v71, 29, v0
	v_not_b32_e32 v66, v63
	v_alignbit_b32 v61, v62, v61, v66
	v_lshlrev_b32_e32 v62, 31, v71
	v_or_b32_e32 v66, 0x33000000, v62
	v_add_lshl_u32 v63, v63, v65, 23
	v_lshrrev_b32_e32 v61, 9, v61
	v_sub_u32_e32 v63, v66, v63
	v_or_b32_e32 v62, 0.5, v62
	v_lshlrev_b32_e32 v65, 23, v65
	v_or_b32_e32 v61, v63, v61
	v_lshrrev_b32_e32 v63, 9, v68
	v_sub_u32_e32 v62, v62, v65
	v_or_b32_e32 v62, v63, v62
	v_mul_f32_e32 v63, 0x3fc90fda, v62
	v_fma_f32 v65, v62, s26, -v63
	v_fmac_f32_e32 v65, 0x33a22168, v62
	v_fmac_f32_e32 v65, 0x3fc90fda, v61
	v_lshrrev_b32_e32 v0, 30, v0
	v_add_f32_e32 v61, v63, v65
	v_add_u32_e32 v0, v72, v0

.LBB0_855:
	v_add_u32_e32 v0, s8, v64
	ds_read_b128 v[88:91], v0
	ds_read_b128 v[92:95], v0 offset:16
	ds_read_b128 v[96:99], v0 offset:32
	ds_read_b128 v[100:103], v0 offset:48
	ds_read_b128 v[104:107], v0 offset:64
	ds_read_b128 v[108:111], v0 offset:80
	ds_read_b128 v[112:115], v0 offset:96
	ds_read_b128 v[116:119], v0 offset:112
	ds_read_b128 v[120:123], v0 offset:128
	ds_read_b128 v[124:127], v0 offset:144
	ds_read_b128 v[128:131], v0 offset:160
	ds_read_b128 v[132:135], v0 offset:176
	s_waitcnt vmcnt(1) lgkmcnt(11)
	ds_read_b128 v[154:157], v0 offset:192
	v_fma_f32 v67, v15, v88, v70
	v_fmac_f32_e32 v67, v17, v89
	v_fmac_f32_e32 v67, v19, v90
	v_fmac_f32_e32 v67, v21, v91
	s_waitcnt lgkmcnt(11)
	ds_read_b128 v[158:161], v0 offset:208
	v_fmac_f32_e32 v67, v23, v92
	v_fmac_f32_e32 v67, v25, v93
	v_fmac_f32_e32 v67, v27, v94
	v_fmac_f32_e32 v67, v29, v95
	s_waitcnt lgkmcnt(11)
	ds_read_b128 v[162:165], v0 offset:224
	v_fmac_f32_e32 v67, v31, v96
	v_fmac_f32_e32 v67, v33, v97
	v_fmac_f32_e32 v67, v35, v98
	v_fmac_f32_e32 v67, v37, v99
	s_waitcnt lgkmcnt(11)
	ds_read_b128 v[166:169], v0 offset:240
	v_fmac_f32_e32 v67, v39, v100
	v_fmac_f32_e32 v67, v40, v101
	v_fmac_f32_e32 v67, v41, v102
	v_fmac_f32_e32 v67, v42, v103
	s_waitcnt lgkmcnt(11)
	v_fmac_f32_e32 v67, v38, v104
	v_fmac_f32_e32 v67, v36, v105
	v_fmac_f32_e32 v67, v34, v106
	v_fmac_f32_e32 v67, v32, v107
	s_waitcnt lgkmcnt(10)
	v_fmac_f32_e32 v67, v30, v108
	v_fmac_f32_e32 v67, v28, v109
	v_fmac_f32_e32 v67, v26, v110
	v_fmac_f32_e32 v67, v43, v111
	s_waitcnt lgkmcnt(9)
	v_fmac_f32_e32 v67, v24, v112
	v_fmac_f32_e32 v67, v22, v113
	v_fmac_f32_e32 v67, v20, v114
	v_fmac_f32_e32 v67, v18, v115
	s_waitcnt lgkmcnt(8)
	v_fmac_f32_e32 v67, v16, v116
	v_fmac_f32_e32 v67, v14, v117
	v_fmac_f32_e32 v67, v44, v118
	v_fmac_f32_e32 v67, v45, v119
	s_waitcnt lgkmcnt(7)
	v_fmac_f32_e32 v67, v46, v120
	v_fmac_f32_e32 v67, v47, v121
	v_fmac_f32_e32 v67, v48, v122
	v_fmac_f32_e32 v67, v49, v123
	s_waitcnt lgkmcnt(6)
	v_fmac_f32_e32 v67, v50, v124
	v_fmac_f32_e32 v67, v51, v125
	v_fmac_f32_e32 v67, v52, v126
	v_fmac_f32_e32 v67, v53, v127
	s_waitcnt lgkmcnt(5)
	v_fmac_f32_e32 v67, v54, v128
	v_fmac_f32_e32 v67, v55, v129
	v_fmac_f32_e32 v67, v56, v130
	v_fmac_f32_e32 v67, v57, v131
	s_waitcnt lgkmcnt(4)
	v_fmac_f32_e32 v67, v58, v132
	v_fmac_f32_e32 v67, v59, v133
	v_fmac_f32_e32 v67, v60, v134
	v_fmac_f32_e32 v67, v61, v135
	s_waitcnt lgkmcnt(3)
	v_fmac_f32_e32 v67, v62, v154
	v_fmac_f32_e32 v67, v63, v155
	v_fmac_f32_e32 v67, v65, v156
	v_fmac_f32_e32 v67, v66, v157
	s_waitcnt lgkmcnt(2)
	v_fmac_f32_e32 v67, v68, v158
	v_fmac_f32_e32 v67, v69, v159
	v_pk_mul_f32 v[158:159], v[2:3], v[160:161]
	s_nop 0
	v_add_f32_e32 v67, v67, v158
	v_add_f32_e32 v67, v67, v159
	s_waitcnt lgkmcnt(1)
	v_pk_mul_f32 v[162:163], v[6:7], v[162:163]
	s_nop 0
	v_add_f32_e32 v67, v67, v162
	v_add_f32_e32 v67, v67, v163
	v_pk_mul_f32 v[162:163], v[8:9], v[164:165]
	s_nop 0
	v_add_f32_e32 v67, v67, v162
	v_add_f32_e32 v67, v67, v163
	s_waitcnt lgkmcnt(0)
	v_pk_mul_f32 v[166:167], v[10:11], v[166:167]
	s_nop 0
	v_add_f32_e32 v0, v67, v166
	v_add_f32_e32 v0, v0, v167
	v_pk_mul_f32 v[166:167], v[12:13], v[168:169]
	s_nop 0
	v_add_f32_e32 v0, v0, v166
	v_add_f32_e32 v0, v0, v167
	s_waitcnt vmcnt(0)
	v_mul_f32_e32 v67, v4, v0
	v_and_b32_e32 v71, 0x7fffffff, v67
	v_cmp_nlt_f32_e64 s[0:1], |v67|, s3
	s_and_saveexec_b64 s[10:11], s[0:1]
	s_xor_b64 s[46:47], exec, s[10:11]
	s_cbranch_execz .LBB0_857
	v_lshrrev_b32_e32 v0, 23, v71
	v_add_u32_e32 v0, 0xffffff88, v0
	v_cmp_lt_u32_e32 vcc, 63, v0
	s_mov_b32 s9, 0x3c439041
	s_nop 0
	v_cndmask_b32_e32 v72, 0, v213, vcc
	v_add_u32_e32 v0, v72, v0
	v_cmp_lt_u32_e64 s[0:1], 31, v0
	s_nop 1
	v_cndmask_b32_e64 v72, 0, v214, s[0:1]
	v_add_u32_e32 v0, v72, v0
	v_cmp_lt_u32_e64 s[40:41], 31, v0
	s_nop 1
	v_cndmask_b32_e64 v72, 0, v214, s[40:41]
	v_add_u32_e32 v86, v72, v0
	v_and_b32_e32 v0, 0x7fffff, v71
	v_or_b32_e32 v84, 0x800000, v0
	v_mad_u64_u32 v[72:73], s[10:11], v84, s36, 0
	v_mov_b32_e32 v0, v73
	v_mad_u64_u32 v[74:75], s[10:11], v84, s9, v[0:1]
	v_mov_b32_e32 v0, v75
	v_mad_u64_u32 v[76:77], s[10:11], v84, s37, v[0:1]
	v_mov_b32_e32 v0, v77
	s_mov_b32 s9, 0xf534ddc0
	v_mad_u64_u32 v[78:79], s[10:11], v84, s9, v[0:1]
	v_mov_b32_e32 v0, v79
	v_mad_u64_u32 v[80:81], s[10:11], v84, s72, v[0:1]
	v_mov_b32_e32 v0, v81
	v_mad_u64_u32 v[82:83], s[10:11], v84, s69, v[0:1]
	v_mov_b32_e32 v0, v83
	v_mad_u64_u32 v[84:85], s[10:11], v84, s97, v[0:1]
	v_cndmask_b32_e32 v73, v82, v78, vcc
	v_cndmask_b32_e32 v0, v84, v80, vcc
	v_cndmask_b32_e32 v77, v85, v82, vcc
	v_cndmask_b32_e64 v75, v0, v73, s[0:1]
	v_cndmask_b32_e64 v0, v77, v0, s[0:1]
	v_cndmask_b32_e32 v77, v80, v76, vcc
	v_cndmask_b32_e64 v73, v73, v77, s[0:1]
	v_cndmask_b32_e32 v74, v78, v74, vcc
	v_cndmask_b32_e64 v0, v0, v75, s[40:41]
	v_cndmask_b32_e64 v75, v75, v73, s[40:41]
	v_sub_u32_e32 v79, 32, v86
	v_cndmask_b32_e64 v77, v77, v74, s[0:1]
	v_alignbit_b32 v80, v0, v75, v79
	v_cmp_eq_u32_e64 s[42:43], 0, v86
	v_cndmask_b32_e64 v73, v73, v77, s[40:41]
	v_cndmask_b32_e32 v72, v76, v72, vcc
	v_cndmask_b32_e64 v0, v80, v0, s[42:43]
	v_alignbit_b32 v78, v75, v73, v79
	v_cndmask_b32_e64 v72, v74, v72, s[0:1]
	v_cndmask_b32_e64 v75, v78, v75, s[42:43]
	v_bfe_u32 v81, v0, 29, 1
	v_cndmask_b32_e64 v72, v77, v72, s[40:41]
	v_alignbit_b32 v78, v0, v75, 30
	v_sub_u32_e32 v82, 0, v81
	v_alignbit_b32 v74, v73, v72, v79
	v_xor_b32_e32 v78, v78, v82
	v_cndmask_b32_e64 v73, v74, v73, s[42:43]
	v_alignbit_b32 v74, v75, v73, 30
	v_ffbh_u32_e32 v75, v78
	v_min_u32_e32 v75, 32, v75
	v_alignbit_b32 v72, v73, v72, 30
	v_xor_b32_e32 v74, v74, v82
	v_sub_u32_e32 v76, 31, v75
	v_xor_b32_e32 v72, v72, v82
	v_alignbit_b32 v77, v78, v74, v76
	v_alignbit_b32 v72, v74, v72, v76
	v_alignbit_b32 v73, v77, v72, 9
	v_ffbh_u32_e32 v74, v73
	v_min_u32_e32 v74, 32, v74
	v_lshrrev_b32_e32 v80, 29, v0
	v_not_b32_e32 v76, v74
	v_alignbit_b32 v72, v73, v72, v76
	v_lshlrev_b32_e32 v73, 31, v80
	v_or_b32_e32 v76, 0x33000000, v73
	v_add_lshl_u32 v74, v74, v75, 23
	v_lshrrev_b32_e32 v72, 9, v72
	v_sub_u32_e32 v74, v76, v74
	v_or_b32_e32 v73, 0.5, v73
	v_lshlrev_b32_e32 v75, 23, v75
	v_or_b32_e32 v72, v74, v72
	v_lshrrev_b32_e32 v74, 9, v77
	v_sub_u32_e32 v73, v73, v75
	v_or_b32_e32 v73, v74, v73
	v_mul_f32_e32 v74, 0x3fc90fda, v73
	v_fma_f32 v75, v73, s26, -v74
	v_fmac_f32_e32 v75, 0x33a22168, v73
	v_fmac_f32_e32 v75, 0x3fc90fda, v72
	v_lshrrev_b32_e32 v0, 30, v0
	v_add_f32_e32 v72, v74, v75
	v_add_u32_e32 v0, v81, v0

.LBB0_860:
	s_lshl_b32 s10, s1, 8
	s_lshl_b32 s11, s0, 8
	v_mov_b32_e32 v144, s11
	v_mov_b32_e32 v145, s10
	ds_read_b128 v[2:5], v144 offset:24832
	ds_read_b128 v[6:9], v144 offset:24848
	ds_read_b128 v[154:157], v144 offset:24864
	ds_read_b128 v[158:161], v144 offset:24880
	ds_read_b128 v[162:165], v145 offset:24832
	ds_read_b128 v[166:169], v145 offset:24848
	ds_read_b128 v[170:173], v145 offset:24864
	ds_read_b128 v[174:177], v145 offset:24880
	ds_read_b128 v[218:221], v144 offset:24896
	ds_read_b128 v[222:225], v144 offset:24912
	ds_read_b128 v[226:229], v144 offset:24928
	ds_read_b128 v[230:233], v144 offset:24944
	ds_read_b128 v[234:237], v145 offset:24896
	ds_read_b128 v[238:241], v145 offset:24912
	ds_read_b128 v[242:245], v145 offset:24928
	ds_read_b128 v[246:249], v145 offset:24944
	s_waitcnt lgkmcnt(8)
	v_fma_f32 v140, v20, v2, 0
	v_fma_f32 v141, v20, v162, 0
	v_fmac_f32_e32 v140, v10, v3
	v_fmac_f32_e32 v141, v10, v163
	v_fmac_f32_e32 v140, v24, v4
	v_fmac_f32_e32 v141, v24, v164
	v_fmac_f32_e32 v140, v26, v5
	v_fmac_f32_e32 v141, v26, v165
	v_fmac_f32_e32 v140, v28, v6
	v_fmac_f32_e32 v141, v28, v166
	v_fmac_f32_e32 v140, v22, v7
	v_fmac_f32_e32 v141, v22, v167
	v_fmac_f32_e32 v140, v32, v8
	v_fmac_f32_e32 v141, v32, v168
	v_fmac_f32_e32 v140, v30, v9
	v_fmac_f32_e32 v141, v30, v169
	v_fmac_f32_e32 v140, v36, v154
	v_fmac_f32_e32 v141, v36, v170
	v_fmac_f32_e32 v140, v34, v155
	v_fmac_f32_e32 v141, v34, v171
	v_fmac_f32_e32 v140, v40, v156
	v_fmac_f32_e32 v141, v40, v172
	v_fmac_f32_e32 v140, v42, v157
	v_fmac_f32_e32 v141, v42, v173
	v_fmac_f32_e32 v140, v44, v158
	v_fmac_f32_e32 v141, v44, v174
	v_fmac_f32_e32 v140, v38, v159
	v_fmac_f32_e32 v141, v38, v175
	v_fmac_f32_e32 v140, v48, v160
	v_fmac_f32_e32 v141, v48, v176
	v_fmac_f32_e32 v140, v46, v161
	v_fmac_f32_e32 v141, v46, v177
	ds_read_b128 v[2:5], v144 offset:24960
	ds_read_b128 v[6:9], v144 offset:24976
	ds_read_b128 v[154:157], v144 offset:24992
	ds_read_b128 v[158:161], v144 offset:25008
	ds_read_b128 v[162:165], v145 offset:24960
	ds_read_b128 v[166:169], v145 offset:24976
	ds_read_b128 v[170:173], v145 offset:24992
	ds_read_b128 v[174:177], v145 offset:25008
	s_waitcnt lgkmcnt(8)
	v_fmac_f32_e32 v140, v52, v218
	v_fmac_f32_e32 v141, v52, v234
	v_fmac_f32_e32 v140, v50, v219
	v_fmac_f32_e32 v141, v50, v235
	v_fmac_f32_e32 v140, v56, v220
	v_fmac_f32_e32 v141, v56, v236
	v_fmac_f32_e32 v140, v58, v221
	v_fmac_f32_e32 v141, v58, v237
	v_fmac_f32_e32 v140, v60, v222
	v_fmac_f32_e32 v141, v60, v238
	v_fmac_f32_e32 v140, v54, v223
	v_fmac_f32_e32 v141, v54, v239
	v_fmac_f32_e32 v140, v64, v224
	v_fmac_f32_e32 v141, v64, v240
	v_fmac_f32_e32 v140, v62, v225
	v_fmac_f32_e32 v141, v62, v241
	v_fmac_f32_e32 v140, v68, v226
	v_fmac_f32_e32 v141, v68, v242
	v_fmac_f32_e32 v140, v66, v227
	v_fmac_f32_e32 v141, v66, v243
	v_fmac_f32_e32 v140, v72, v228
	v_fmac_f32_e32 v141, v72, v244
	v_fmac_f32_e32 v140, v74, v229
	v_fmac_f32_e32 v141, v74, v245
	v_fmac_f32_e32 v140, v76, v230
	v_fmac_f32_e32 v141, v76, v246
	v_fmac_f32_e32 v140, v70, v231
	v_fmac_f32_e32 v141, v70, v247
	v_fmac_f32_e32 v140, v80, v232
	v_fmac_f32_e32 v141, v80, v248
	v_fmac_f32_e32 v140, v78, v233
	v_fmac_f32_e32 v141, v78, v249
	ds_read_b128 v[218:221], v144 offset:25024
	ds_read_b128 v[222:225], v144 offset:25040
	ds_read_b128 v[226:229], v144 offset:25056
	ds_read_b128 v[230:233], v144 offset:25072
	ds_read_b128 v[234:237], v145 offset:25024
	ds_read_b128 v[238:241], v145 offset:25040
	ds_read_b128 v[242:245], v145 offset:25056
	ds_read_b128 v[246:249], v145 offset:25072
	s_waitcnt lgkmcnt(8)
	v_fmac_f32_e32 v140, v84, v2
	v_fmac_f32_e32 v141, v84, v162
	v_fmac_f32_e32 v140, v82, v3
	v_fmac_f32_e32 v141, v82, v163
	v_fmac_f32_e32 v140, v88, v4
	v_fmac_f32_e32 v141, v88, v164
	v_fmac_f32_e32 v140, v90, v5
	v_fmac_f32_e32 v141, v90, v165
	v_fmac_f32_e32 v140, v92, v6
	v_fmac_f32_e32 v141, v92, v166
	v_fmac_f32_e32 v140, v86, v7
	v_fmac_f32_e32 v141, v86, v167
	v_fmac_f32_e32 v140, v96, v8
	v_fmac_f32_e32 v141, v96, v168
	v_fmac_f32_e32 v140, v94, v9
	v_fmac_f32_e32 v141, v94, v169
	v_fmac_f32_e32 v140, v100, v154
	v_fmac_f32_e32 v141, v100, v170
	v_fmac_f32_e32 v140, v98, v155
	v_fmac_f32_e32 v141, v98, v171
	v_fmac_f32_e32 v140, v104, v156
	v_fmac_f32_e32 v141, v104, v172
	v_fmac_f32_e32 v140, v106, v157
	v_fmac_f32_e32 v141, v106, v173
	v_fmac_f32_e32 v140, v108, v158
	v_fmac_f32_e32 v141, v108, v174
	v_fmac_f32_e32 v140, v102, v159
	v_fmac_f32_e32 v141, v102, v175
	v_fmac_f32_e32 v140, v112, v160
	v_fmac_f32_e32 v141, v112, v176
	v_fmac_f32_e32 v140, v110, v161
	v_fmac_f32_e32 v141, v110, v177
	s_waitcnt lgkmcnt(0)
	v_fmac_f32_e32 v140, v116, v218
	v_fmac_f32_e32 v141, v116, v234
	v_fmac_f32_e32 v140, v114, v219
	v_fmac_f32_e32 v141, v114, v235
	v_fmac_f32_e32 v140, v120, v220
	v_fmac_f32_e32 v141, v120, v236
	v_fmac_f32_e32 v140, v122, v221
	v_fmac_f32_e32 v141, v122, v237
	v_fmac_f32_e32 v140, v124, v222
	v_fmac_f32_e32 v141, v124, v238
	v_fmac_f32_e32 v140, v118, v223
	v_fmac_f32_e32 v141, v118, v239
	v_fmac_f32_e32 v140, v128, v224
	v_fmac_f32_e32 v141, v128, v240
	v_fmac_f32_e32 v140, v126, v225
	v_fmac_f32_e32 v141, v126, v241
	v_fmac_f32_e32 v140, v132, v226
	v_fmac_f32_e32 v141, v132, v242
	v_fmac_f32_e32 v140, v130, v227
	v_fmac_f32_e32 v141, v130, v243
	v_fmac_f32_e32 v140, v134, v228
	v_fmac_f32_e32 v141, v134, v244
	v_fmac_f32_e32 v140, v12, v229
	v_fmac_f32_e32 v141, v12, v245
	v_fmac_f32_e32 v140, v136, v230
	v_fmac_f32_e32 v141, v136, v246
	v_fmac_f32_e32 v140, v14, v231
	v_fmac_f32_e32 v141, v14, v247
	v_fmac_f32_e32 v140, v16, v232
	v_fmac_f32_e32 v141, v16, v248
	v_fmac_f32_e32 v140, v18, v233
	v_fmac_f32_e32 v141, v18, v249
	v_mov_b32_e32 v2, v140
	v_mov_b32_e32 v3, v141
	s_or_b64 s[10:11], s[0:1], s[38:39]
	s_add_i32 s0, s0, 2
	s_add_i32 s1, s1, 2
	v_cvt_f32_i32_e32 v4, s11
	v_cvt_f32_i32_e32 v5, s10
	v_xor_b32_e32 v4, 0x80000000, v4
	v_xor_b32_e32 v6, 0x80000000, v5
	v_div_scale_f32 v5, s[10:11], v143, v143, v4
	v_rcp_f32_e32 v7, v5
	s_nop 0
	v_fma_f32 v8, -v5, v7, 1.0
	v_fmac_f32_e32 v7, v8, v7
	v_div_scale_f32 v8, vcc, v4, v143, v4
	v_mul_f32_e32 v9, v8, v7
	v_fma_f32 v140, -v5, v9, v8
	v_fmac_f32_e32 v9, v140, v7
	v_fma_f32 v5, -v5, v9, v8
	v_div_fmas_f32 v5, v5, v7, v9
	v_div_fixup_f32 v5, v5, v143, v4
	v_div_scale_f32 v4, s[10:11], v143, v143, v6
	v_rcp_f32_e32 v7, v4
	s_nop 0
	v_fma_f32 v8, -v4, v7, 1.0
	v_fmac_f32_e32 v7, v8, v7
	v_div_scale_f32 v8, vcc, v6, v143, v6
	v_mul_f32_e32 v9, v8, v7
	v_fma_f32 v140, -v4, v9, v8
	v_fmac_f32_e32 v9, v140, v7
	v_fma_f32 v4, -v4, v9, v8
	v_div_fmas_f32 v4, v4, v7, v9
	v_div_fixup_f32 v4, v4, v143, v6
	v_pk_mul_f32 v[4:5], v[138:139], v[4:5]
	s_nop 0
	v_mul_f32_e32 v6, 0x3fb8aa3b, v5
	v_fma_f32 v7, v5, s96, -v6
	v_rndne_f32_e32 v8, v6
	v_fmac_f32_e32 v7, 0x32a5705f, v5
	v_sub_f32_e32 v6, v6, v8
	v_add_f32_e32 v6, v6, v7
	v_exp_f32_e32 v6, v6
	v_cvt_i32_f32_e32 v7, v8
	v_cmp_ngt_f32_e32 vcc, s68, v5
	v_ldexp_f32 v6, v6, v7
	s_nop 0
	v_cndmask_b32_e32 v6, 0, v6, vcc
	v_cmp_nlt_f32_e32 vcc, s2, v5
	s_nop 1
	v_cndmask_b32_e32 v5, v204, v6, vcc
	v_mul_f32_e32 v6, 0x3fb8aa3b, v4
	v_fma_f32 v7, v4, s96, -v6
	v_rndne_f32_e32 v8, v6
	v_fmac_f32_e32 v7, 0x32a5705f, v4
	v_sub_f32_e32 v6, v6, v8
	v_add_f32_e32 v6, v6, v7
	v_exp_f32_e32 v6, v6
	v_cvt_i32_f32_e32 v7, v8
	v_cmp_ngt_f32_e32 vcc, s68, v4
	v_ldexp_f32 v6, v6, v7
	s_nop 0
	v_cndmask_b32_e32 v6, 0, v6, vcc
	v_cmp_nlt_f32_e32 vcc, s2, v4
	s_nop 1
	v_cndmask_b32_e32 v4, v204, v6, vcc
	v_pk_mul_f32 v[2:3], v[4:5], v[2:3]
	s_nop 0
	v_cvt_pk_bf16_f32 v2, v2, v3
	v_add_u32_e32 v3, s9, v0
	s_add_i32 s9, s9, 4
	s_cmpk_eq_i32 s9, 0x80
	ds_write_b32 v3, v2
	s_cbranch_scc0 .LBB0_860
	v_lshlrev_b32_e32 v0, 4, v142
	v_and_b32_e32 v0, 0x70, v0
	v_ashrrev_i32_e32 v8, 3, v142
	s_movk_i32 s11, 0x90
	v_mad_u64_u32 v[2:3], s[0:1], v8, s11, v[0:1]
	s_mul_i32 s1, s44, 0x440000
	s_mul_hi_i32 s0, s44, 0x440000
	s_add_u32 s9, s78, s1
	s_addc_u32 s10, s79, s0
	s_and_b64 s[0:1], s[28:29], exec
	s_cselect_b32 s0, 0x40000, 0
	s_add_u32 s9, s9, s0
	s_addc_u32 s10, s10, 0
	s_ashr_i32 s39, s38, 31
	s_lshl_b64 s[0:1], s[38:39], 1
	s_add_u32 s0, s9, s0
	s_addc_u32 s1, s10, s1
	s_waitcnt lgkmcnt(0)
	s_barrier
	ds_read_b128 v[2:5], v2 offset:41216
	v_lshl_add_u64 v[6:7], s[0:1], 0, v[0:1]
	v_add_u32_e32 v8, s8, v8
	s_and_b64 s[0:1], s[28:29], exec
	v_ashrrev_i32_e32 v9, 31, v8
	s_cselect_b32 s9, 12, 8
	v_lshlrev_b64 v[8:9], s9, v[8:9]
	v_lshl_add_u64 v[8:9], v[8:9], 1, v[6:7]
	s_waitcnt lgkmcnt(0)
	global_store_dwordx4 v[8:9], v[2:5], off
	s_nop 1
	v_add_u32_e32 v2, 0x100, v142
	v_ashrrev_i32_e32 v8, 3, v2
	v_mad_u64_u32 v[2:3], s[0:1], v8, s11, v[0:1]
	ds_read_b128 v[2:5], v2 offset:41216
	v_add_u32_e32 v8, s8, v8
	v_ashrrev_i32_e32 v9, 31, v8
	v_lshlrev_b64 v[8:9], s9, v[8:9]
	v_lshl_add_u64 v[8:9], v[8:9], 1, v[6:7]
	s_waitcnt lgkmcnt(0)
	global_store_dwordx4 v[8:9], v[2:5], off
	s_nop 1
	v_add_u32_e32 v2, 0x200, v142
	v_ashrrev_i32_e32 v8, 3, v2
	v_mad_u64_u32 v[2:3], s[0:1], v8, s11, v[0:1]
	ds_read_b128 v[2:5], v2 offset:41216
	v_add_u32_e32 v8, s8, v8
	v_ashrrev_i32_e32 v9, 31, v8
	v_lshlrev_b64 v[8:9], s9, v[8:9]
	v_lshl_add_u64 v[8:9], v[8:9], 1, v[6:7]
	s_waitcnt lgkmcnt(0)
	global_store_dwordx4 v[8:9], v[2:5], off
	s_nop 1
	v_add_u32_e32 v2, 0x300, v142
	v_ashrrev_i32_e32 v8, 3, v2
	v_mad_u64_u32 v[2:3], s[0:1], v8, s11, v[0:1]
	ds_read_b128 v[2:5], v2 offset:41216
	v_add_u32_e32 v8, s8, v8
	v_ashrrev_i32_e32 v9, 31, v8
	v_lshlrev_b64 v[8:9], s9, v[8:9]
	v_lshl_add_u64 v[8:9], v[8:9], 1, v[6:7]
	s_waitcnt lgkmcnt(0)
	global_store_dwordx4 v[8:9], v[2:5], off
	s_nop 1
	v_add_u32_e32 v2, 0x400, v142
	v_ashrrev_i32_e32 v8, 3, v2
	v_mad_u64_u32 v[2:3], s[0:1], v8, s11, v[0:1]
	ds_read_b128 v[2:5], v2 offset:41216
	v_add_u32_e32 v8, s8, v8
	v_ashrrev_i32_e32 v9, 31, v8
	v_lshlrev_b64 v[8:9], s9, v[8:9]
	v_lshl_add_u64 v[8:9], v[8:9], 1, v[6:7]
	s_waitcnt lgkmcnt(0)
	global_store_dwordx4 v[8:9], v[2:5], off
	s_nop 1
	v_add_u32_e32 v2, 0x500, v142
	v_ashrrev_i32_e32 v8, 3, v2
	v_mad_u64_u32 v[2:3], s[0:1], v8, s11, v[0:1]
	ds_read_b128 v[2:5], v2 offset:41216
	v_add_u32_e32 v8, s8, v8
	v_ashrrev_i32_e32 v9, 31, v8
	v_lshlrev_b64 v[8:9], s9, v[8:9]
	v_lshl_add_u64 v[8:9], v[8:9], 1, v[6:7]
	s_waitcnt lgkmcnt(0)
	global_store_dwordx4 v[8:9], v[2:5], off
	s_nop 1
	v_add_u32_e32 v2, 0x600, v142
	v_ashrrev_i32_e32 v8, 3, v2
	v_mad_u64_u32 v[2:3], s[0:1], v8, s11, v[0:1]
	ds_read_b128 v[2:5], v2 offset:41216
	v_add_u32_e32 v8, s8, v8
	v_ashrrev_i32_e32 v9, 31, v8
	v_lshlrev_b64 v[8:9], s9, v[8:9]
	v_lshl_add_u64 v[8:9], v[8:9], 1, v[6:7]
	s_waitcnt lgkmcnt(0)
	global_store_dwordx4 v[8:9], v[2:5], off
	s_nop 1
	v_add_u32_e32 v2, 0x700, v142
	v_ashrrev_i32_e32 v8, 3, v2
	v_mad_u64_u32 v[2:3], s[0:1], v8, s11, v[0:1]
	ds_read_b128 v[2:5], v2 offset:41216
	v_add_u32_e32 v8, s8, v8
	v_ashrrev_i32_e32 v9, 31, v8
	v_lshlrev_b64 v[8:9], s9, v[8:9]
	v_lshl_add_u64 v[6:7], v[8:9], 1, v[6:7]
	s_waitcnt lgkmcnt(0)
	global_store_dwordx4 v[6:7], v[2:5], off
	s_barrier
	s_branch .LBB0_746
